# 16x16x32 GEMM loops: staging write pairs after MFMA 13 of k-step 0 and MFMAs 1,5,9 of k-step 1
# speedup vs baseline: 1.0134x; 1.0033x over previous
; #define MFMA(a, b, c) __builtin_amdgcn_mfma_f32_32x32x16_bf16((a), (b), (c), 0, 0, 0)
; template <bool SWAP, class Epi>
; DI void gemm_tile(const u16* __restrict__ A, int lda, const u16* __restrict__ Bt, int ldb, int K, int m0, int n0, char* smem, Epi&& epi) {
;     ...
;   auto compute = [&](int buf) __attribute__((always_inline)) {
;     bf16x8 af[2][2], bfr[2][2];
;     af[0][0] = *(const bf16x8*)(Asb + buf * 128 * 72);
;     af[0][1] = *(const bf16x8*)(Asb + buf * 128 * 72 + 32 * 72);
;     bfr[0][0] = *(const bf16x8*)(Bsb + buf * 128 * 72);
;     bfr[0][1] = *(const bf16x8*)(Bsb + buf * 128 * 72 + 32 * 72);
; #pragma unroll
;     for (int ks = 0; ks < 4; ++ks) {
;       const int c = ks & 1, n = c ^ 1;
;       if (ks < 3) {
;         af[n][0] = *(const bf16x8*)(Asb + buf * 128 * 72 + (ks + 1) * 16);
;         af[n][1] = *(const bf16x8*)(Asb + buf * 128 * 72 + 32 * 72 + (ks + 1) * 16);
;         bfr[n][0] = *(const bf16x8*)(Bsb + buf * 128 * 72 + (ks + 1) * 16);
;         bfr[n][1] = *(const bf16x8*)(Bsb + buf * 128 * 72 + 32 * 72 + (ks + 1) * 16);
;       }
;       __builtin_amdgcn_sched_barrier(0);
; #pragma unroll
;       for (int mi = 0; mi < 2; ++mi)
; #pragma unroll
;         for (int ni = 0; ni < 2; ++ni) {
;           if (SWAP) acc[mi][ni] = MFMA(bfr[c][ni], af[c][mi], acc[mi][ni]);
;           else acc[mi][ni] = MFMA(af[c][mi], bfr[c][ni], acc[mi][ni]);
;         }
;       __builtin_amdgcn_sched_barrier(0);
;     }
;   };
;   for (int kt = 0; kt < KT; kt += 2) {
;     if (kt + 2 < KT) {
;       const int k0 = (kt + 2) << 6;
; #pragma unroll
;       for (int i = 0; i < 4; ++i) { ra0[i] = *(const u32x4*)(ag + (size_t)i * 32 * lda + k0); rb0[i] = *(const u32x4*)(bg + (size_t)i * 32 * ldb + k0); }
;     }
;     compute(0);
; #pragma unroll
;     for (int i = 0; i < 4; ++i) { *(u32x4*)(asw + 128 * 72 + 32 * i * 72) = ra1[i]; *(u32x4*)(bsw + 128 * 72 + 32 * i * 72) = rb1[i]; }
;     __syncthreads();
;     if (kt + 3 < KT) {
;       const int k0 = (kt + 3) << 6;
; #pragma unroll
;       for (int i = 0; i < 4; ++i) { ra1[i] = *(const u32x4*)(ag + (size_t)i * 32 * lda + k0); rb1[i] = *(const u32x4*)(bg + (size_t)i * 32 * ldb + k0); }
;     }
;     compute(1);
.LBB0_387:
	global_load_dwordx4 v[66:69], v194, s[100:101] offset:256
	global_load_dwordx4 v[70:73], v190, s[98:99] offset:256
	global_load_dwordx4 v[74:77], v195, s[100:101] offset:256
	global_load_dwordx4 v[78:81], v191, s[98:99] offset:256
	global_load_dwordx4 v[82:85], v196, s[100:101] offset:256
	global_load_dwordx4 v[86:89], v192, s[98:99] offset:256
	global_load_dwordx4 v[90:93], v197, s[100:101] offset:256
	global_load_dwordx4 v[94:97], v193, s[98:99] offset:256
	ds_read_b128 v[170:173], v150 offset:36880
	ds_read_b128 v[154:157], v149 offset:16
	ds_read_b128 v[158:161], v149 offset:2320
	ds_read_b128 v[174:177], v150 offset:39184
	ds_read_b128 v[162:165], v149 offset:4624
	ds_read_b128 v[166:169], v149 offset:6928
	ds_read_b128 v[178:181], v150 offset:41488
	ds_read_b128 v[182:185], v150 offset:43792
	s_waitcnt lgkmcnt(6)
	v_mfma_f32_16x16x32_bf16 v[50:53], v[170:173], v[154:157], v[50:53]
	s_waitcnt lgkmcnt(5)
	v_mfma_f32_16x16x32_bf16 v[54:57], v[170:173], v[158:161], v[54:57]
	s_waitcnt lgkmcnt(4)
	v_mfma_f32_16x16x32_bf16 v[58:61], v[174:177], v[154:157], v[58:61]
	v_mfma_f32_16x16x32_bf16 v[62:65], v[174:177], v[158:161], v[62:65]
	ds_read_b128 v[214:217], v150 offset:36944
	ds_read_b128 v[198:201], v149 offset:80
	ds_read_b128 v[202:205], v149 offset:2384
	ds_read_b128 v[218:221], v150 offset:39248
	s_waitcnt lgkmcnt(7)
	v_mfma_f32_16x16x32_bf16 v[18:21], v[170:173], v[162:165], v[18:21]
	v_mfma_f32_16x16x32_bf16 v[26:29], v[174:177], v[162:165], v[26:29]
	s_waitcnt lgkmcnt(6)
	v_mfma_f32_16x16x32_bf16 v[22:25], v[170:173], v[166:169], v[22:25]
	v_mfma_f32_16x16x32_bf16 v[30:33], v[174:177], v[166:169], v[30:33]
	ds_read_b128 v[206:209], v149 offset:4688
	ds_read_b128 v[210:213], v149 offset:6992
	ds_read_b128 v[222:225], v150 offset:41552
	ds_read_b128 v[226:229], v150 offset:43856
	s_waitcnt lgkmcnt(9)
	v_mfma_f32_16x16x32_bf16 v[34:37], v[178:181], v[154:157], v[34:37]
	v_mfma_f32_16x16x32_bf16 v[38:41], v[178:181], v[158:161], v[38:41]
	v_mfma_f32_16x16x32_bf16 v[2:5], v[178:181], v[162:165], v[2:5]
	v_mfma_f32_16x16x32_bf16 v[6:9], v[178:181], v[166:169], v[6:9]
	s_waitcnt lgkmcnt(8)
	v_mfma_f32_16x16x32_bf16 v[42:45], v[182:185], v[154:157], v[42:45]
	v_mfma_f32_16x16x32_bf16 v[46:49], v[182:185], v[158:161], v[46:49]
	s_waitcnt vmcnt(14)
	ds_write_b128 v146, v[98:101] offset:18448
	ds_write_b128 v146, v[102:105] offset:55312
	v_mfma_f32_16x16x32_bf16 v[10:13], v[182:185], v[162:165], v[10:13]
	v_mfma_f32_16x16x32_bf16 v[14:17], v[182:185], v[166:169], v[14:17]
	s_waitcnt lgkmcnt(8)
	v_mfma_f32_16x16x32_bf16 v[50:53], v[214:217], v[198:201], v[50:53]
	s_waitcnt lgkmcnt(7)
	v_mfma_f32_16x16x32_bf16 v[54:57], v[214:217], v[202:205], v[54:57]
	s_waitcnt vmcnt(12)
	ds_write_b128 v146, v[106:109] offset:23056
	ds_write_b128 v146, v[110:113] offset:59920
	s_waitcnt lgkmcnt(8)
	v_mfma_f32_16x16x32_bf16 v[58:61], v[218:221], v[198:201], v[58:61]
	v_mfma_f32_16x16x32_bf16 v[62:65], v[218:221], v[202:205], v[62:65]
	s_waitcnt lgkmcnt(7)
	v_mfma_f32_16x16x32_bf16 v[18:21], v[214:217], v[206:209], v[18:21]
	v_mfma_f32_16x16x32_bf16 v[26:29], v[218:221], v[206:209], v[26:29]
	s_waitcnt vmcnt(10)
	ds_write_b128 v146, v[114:117] offset:27664
	ds_write_b128 v146, v[118:121] offset:64528
	s_waitcnt lgkmcnt(8)
	v_mfma_f32_16x16x32_bf16 v[22:25], v[214:217], v[210:213], v[22:25]
	v_mfma_f32_16x16x32_bf16 v[30:33], v[218:221], v[210:213], v[30:33]
	s_waitcnt lgkmcnt(7)
	v_mfma_f32_16x16x32_bf16 v[34:37], v[222:225], v[198:201], v[34:37]
	v_mfma_f32_16x16x32_bf16 v[38:41], v[222:225], v[202:205], v[38:41]
	s_waitcnt vmcnt(8)
	ds_write_b128 v146, v[122:125] offset:32272
	ds_write_b128 v147, v[126:129] offset:32256
	v_mfma_f32_16x16x32_bf16 v[2:5], v[222:225], v[206:209], v[2:5]
	v_mfma_f32_16x16x32_bf16 v[6:9], v[222:225], v[210:213], v[6:9]
	s_waitcnt lgkmcnt(8)
	v_mfma_f32_16x16x32_bf16 v[42:45], v[226:229], v[198:201], v[42:45]
	v_mfma_f32_16x16x32_bf16 v[46:49], v[226:229], v[202:205], v[46:49]
	v_mfma_f32_16x16x32_bf16 v[10:13], v[226:229], v[206:209], v[10:13]
	v_mfma_f32_16x16x32_bf16 v[14:17], v[226:229], v[210:213], v[14:17]
	s_waitcnt lgkmcnt(0)
	s_barrier
	global_load_dwordx4 v[98:101], v194, s[100:101] offset:384
	global_load_dwordx4 v[102:105], v190, s[98:99] offset:384
	global_load_dwordx4 v[106:109], v195, s[100:101] offset:384
	global_load_dwordx4 v[110:113], v191, s[98:99] offset:384
	global_load_dwordx4 v[114:117], v196, s[100:101] offset:384
	global_load_dwordx4 v[118:121], v192, s[98:99] offset:384
	global_load_dwordx4 v[122:125], v197, s[100:101] offset:384
	global_load_dwordx4 v[126:129], v193, s[98:99] offset:384
	ds_read_b128 v[170:173], v150 offset:55312
	ds_read_b128 v[154:157], v149 offset:18448
	ds_read_b128 v[158:161], v149 offset:20752
	ds_read_b128 v[174:177], v150 offset:57616
	ds_read_b128 v[162:165], v149 offset:23056
	ds_read_b128 v[166:169], v149 offset:25360
	ds_read_b128 v[178:181], v150 offset:59920
	ds_read_b128 v[182:185], v150 offset:62224
	s_waitcnt lgkmcnt(6)
	v_mfma_f32_16x16x32_bf16 v[50:53], v[170:173], v[154:157], v[50:53]
	s_waitcnt lgkmcnt(5)
	v_mfma_f32_16x16x32_bf16 v[54:57], v[170:173], v[158:161], v[54:57]
	s_waitcnt lgkmcnt(4)
	v_mfma_f32_16x16x32_bf16 v[58:61], v[174:177], v[154:157], v[58:61]
	v_mfma_f32_16x16x32_bf16 v[62:65], v[174:177], v[158:161], v[62:65]
	ds_read_b128 v[214:217], v150 offset:55376
	ds_read_b128 v[198:201], v149 offset:18512
	ds_read_b128 v[202:205], v149 offset:20816
	ds_read_b128 v[218:221], v150 offset:57680
	s_waitcnt lgkmcnt(7)
	v_mfma_f32_16x16x32_bf16 v[18:21], v[170:173], v[162:165], v[18:21]
	v_mfma_f32_16x16x32_bf16 v[26:29], v[174:177], v[162:165], v[26:29]
	s_waitcnt lgkmcnt(6)
; #define MFMA(a, b, c) __builtin_amdgcn_mfma_f32_32x32x16_bf16((a), (b), (c), 0, 0, 0)
; template <bool SWAP, class Epi>
; DI void gemm_tile(const u16* __restrict__ A, int lda, const u16* __restrict__ Bt, int ldb, int K, int m0, int n0, char* smem, Epi&& epi) {
;     ...
;   auto compute = [&](int buf) __attribute__((always_inline)) {
;     bf16x8 af[2][2], bfr[2][2];
;     af[0][0] = *(const bf16x8*)(Asb + buf * 128 * 72);
;     af[0][1] = *(const bf16x8*)(Asb + buf * 128 * 72 + 32 * 72);
;     bfr[0][0] = *(const bf16x8*)(Bsb + buf * 128 * 72);
;     bfr[0][1] = *(const bf16x8*)(Bsb + buf * 128 * 72 + 32 * 72);
; #pragma unroll
;     for (int ks = 0; ks < 4; ++ks) {
;       const int c = ks & 1, n = c ^ 1;
;       if (ks < 3) {
;         af[n][0] = *(const bf16x8*)(Asb + buf * 128 * 72 + (ks + 1) * 16);
;         af[n][1] = *(const bf16x8*)(Asb + buf * 128 * 72 + 32 * 72 + (ks + 1) * 16);
;         bfr[n][0] = *(const bf16x8*)(Bsb + buf * 128 * 72 + (ks + 1) * 16);
;         bfr[n][1] = *(const bf16x8*)(Bsb + buf * 128 * 72 + 32 * 72 + (ks + 1) * 16);
;       }
;       __builtin_amdgcn_sched_barrier(0);
; #pragma unroll
;       for (int mi = 0; mi < 2; ++mi)
; #pragma unroll
;         for (int ni = 0; ni < 2; ++ni) {
;           if (SWAP) acc[mi][ni] = MFMA(bfr[c][ni], af[c][mi], acc[mi][ni]);
;           else acc[mi][ni] = MFMA(af[c][mi], bfr[c][ni], acc[mi][ni]);
;         }
;       __builtin_amdgcn_sched_barrier(0);
;     }
;   };
;   for (int kt = 0; kt < KT; kt += 2) {
;     if (kt + 2 < KT) {
;       const int k0 = (kt + 2) << 6;
; #pragma unroll
;       for (int i = 0; i < 4; ++i) { ra0[i] = *(const u32x4*)(ag + (size_t)i * 32 * lda + k0); rb0[i] = *(const u32x4*)(bg + (size_t)i * 32 * ldb + k0); }
;     }
;     compute(0);
; #pragma unroll
;     for (int i = 0; i < 4; ++i) { *(u32x4*)(asw + 128 * 72 + 32 * i * 72) = ra1[i]; *(u32x4*)(bsw + 128 * 72 + 32 * i * 72) = rb1[i]; }
;     __syncthreads();
;     if (kt + 3 < KT) {
;       const int k0 = (kt + 3) << 6;
; #pragma unroll
;       for (int i = 0; i < 4; ++i) { ra1[i] = *(const u32x4*)(ag + (size_t)i * 32 * lda + k0); rb1[i] = *(const u32x4*)(bg + (size_t)i * 32 * ldb + k0); }
;     }
;     compute(1);
;     if (kt + 2 < KT) {
; #pragma unroll
;       for (int i = 0; i < 4; ++i) { *(u32x4*)(asw + 32 * i * 72) = ra0[i]; *(u32x4*)(bsw + 32 * i * 72) = rb0[i]; }
;     }
;     __syncthreads();
;   }
	v_mfma_f32_16x16x32_bf16 v[22:25], v[170:173], v[166:169], v[22:25]
	v_mfma_f32_16x16x32_bf16 v[30:33], v[174:177], v[166:169], v[30:33]
	ds_read_b128 v[206:209], v149 offset:23120
	ds_read_b128 v[210:213], v149 offset:25424
	ds_read_b128 v[222:225], v150 offset:59984
	ds_read_b128 v[226:229], v150 offset:62288
	s_waitcnt lgkmcnt(9)
	v_mfma_f32_16x16x32_bf16 v[34:37], v[178:181], v[154:157], v[34:37]
	v_mfma_f32_16x16x32_bf16 v[38:41], v[178:181], v[158:161], v[38:41]
	v_mfma_f32_16x16x32_bf16 v[2:5], v[178:181], v[162:165], v[2:5]
	v_mfma_f32_16x16x32_bf16 v[6:9], v[178:181], v[166:169], v[6:9]
	s_waitcnt lgkmcnt(8)
	v_mfma_f32_16x16x32_bf16 v[42:45], v[182:185], v[154:157], v[42:45]
	v_mfma_f32_16x16x32_bf16 v[46:49], v[182:185], v[158:161], v[46:49]
	s_waitcnt vmcnt(14)
	ds_write_b128 v146, v[66:69] offset:16
	ds_write_b128 v146, v[70:73] offset:36880
	v_mfma_f32_16x16x32_bf16 v[10:13], v[182:185], v[162:165], v[10:13]
	v_mfma_f32_16x16x32_bf16 v[14:17], v[182:185], v[166:169], v[14:17]
	s_waitcnt lgkmcnt(8)
	v_mfma_f32_16x16x32_bf16 v[50:53], v[214:217], v[198:201], v[50:53]
	s_waitcnt lgkmcnt(7)
	v_mfma_f32_16x16x32_bf16 v[54:57], v[214:217], v[202:205], v[54:57]
	s_waitcnt vmcnt(12)
	ds_write_b128 v146, v[74:77] offset:4624
	ds_write_b128 v146, v[78:81] offset:41488
	s_waitcnt lgkmcnt(8)
	v_mfma_f32_16x16x32_bf16 v[58:61], v[218:221], v[198:201], v[58:61]
	v_mfma_f32_16x16x32_bf16 v[62:65], v[218:221], v[202:205], v[62:65]
	s_waitcnt lgkmcnt(7)
	v_mfma_f32_16x16x32_bf16 v[18:21], v[214:217], v[206:209], v[18:21]
	v_mfma_f32_16x16x32_bf16 v[26:29], v[218:221], v[206:209], v[26:29]
	s_waitcnt vmcnt(10)
	ds_write_b128 v146, v[82:85] offset:9232
	ds_write_b128 v146, v[86:89] offset:46096
	s_waitcnt lgkmcnt(8)
	v_mfma_f32_16x16x32_bf16 v[22:25], v[214:217], v[210:213], v[22:25]
	v_mfma_f32_16x16x32_bf16 v[30:33], v[218:221], v[210:213], v[30:33]
	s_waitcnt lgkmcnt(7)
	v_mfma_f32_16x16x32_bf16 v[34:37], v[222:225], v[198:201], v[34:37]
	v_mfma_f32_16x16x32_bf16 v[38:41], v[222:225], v[202:205], v[38:41]
	s_waitcnt vmcnt(8)
	ds_write_b128 v146, v[90:93] offset:13840
	ds_write_b128 v146, v[94:97] offset:50704
	v_mfma_f32_16x16x32_bf16 v[2:5], v[222:225], v[206:209], v[2:5]
	v_mfma_f32_16x16x32_bf16 v[6:9], v[222:225], v[210:213], v[6:9]
	s_waitcnt lgkmcnt(8)
	v_mfma_f32_16x16x32_bf16 v[42:45], v[226:229], v[198:201], v[42:45]
	v_mfma_f32_16x16x32_bf16 v[46:49], v[226:229], v[202:205], v[46:49]
	v_mfma_f32_16x16x32_bf16 v[10:13], v[226:229], v[206:209], v[10:13]
	v_mfma_f32_16x16x32_bf16 v[14:17], v[226:229], v[210:213], v[14:17]
	s_add_i32 s24, s24, 2
	s_add_u32 s98, s98, 256
	s_addc_u32 s99, s99, 0
	s_add_u32 s100, s100, 256
	s_addc_u32 s101, s101, 0
	s_waitcnt lgkmcnt(0)
	s_barrier
	s_cmp_lt_u32 s24, 30
	s_cbranch_scc1 .LBB0_387
	ds_read_b128 v[170:173], v150 offset:36880
	ds_read_b128 v[154:157], v149 offset:16
	ds_read_b128 v[158:161], v149 offset:2320
	ds_read_b128 v[174:177], v150 offset:39184
	ds_read_b128 v[162:165], v149 offset:4624
	ds_read_b128 v[166:169], v149 offset:6928
	ds_read_b128 v[178:181], v150 offset:41488
	ds_read_b128 v[182:185], v150 offset:43792
	s_waitcnt lgkmcnt(6)
	v_mfma_f32_16x16x32_bf16 v[50:53], v[170:173], v[154:157], v[50:53]
	s_waitcnt lgkmcnt(5)
	v_mfma_f32_16x16x32_bf16 v[54:57], v[170:173], v[158:161], v[54:57]
	s_waitcnt lgkmcnt(4)
	v_mfma_f32_16x16x32_bf16 v[58:61], v[174:177], v[154:157], v[58:61]
	v_mfma_f32_16x16x32_bf16 v[62:65], v[174:177], v[158:161], v[62:65]
	ds_read_b128 v[214:217], v150 offset:36944
	ds_read_b128 v[198:201], v149 offset:80
	ds_read_b128 v[202:205], v149 offset:2384
	ds_read_b128 v[218:221], v150 offset:39248
	s_waitcnt lgkmcnt(7)
	v_mfma_f32_16x16x32_bf16 v[18:21], v[170:173], v[162:165], v[18:21]
	v_mfma_f32_16x16x32_bf16 v[26:29], v[174:177], v[162:165], v[26:29]
	s_waitcnt lgkmcnt(6)
	v_mfma_f32_16x16x32_bf16 v[22:25], v[170:173], v[166:169], v[22:25]
	v_mfma_f32_16x16x32_bf16 v[30:33], v[174:177], v[166:169], v[30:33]
	ds_read_b128 v[206:209], v149 offset:4688
	ds_read_b128 v[210:213], v149 offset:6992
	ds_read_b128 v[222:225], v150 offset:41552
	ds_read_b128 v[226:229], v150 offset:43856
	s_waitcnt lgkmcnt(9)
	v_mfma_f32_16x16x32_bf16 v[34:37], v[178:181], v[154:157], v[34:37]
	v_mfma_f32_16x16x32_bf16 v[38:41], v[178:181], v[158:161], v[38:41]
	v_mfma_f32_16x16x32_bf16 v[2:5], v[178:181], v[162:165], v[2:5]
	v_mfma_f32_16x16x32_bf16 v[6:9], v[178:181], v[166:169], v[6:9]
	s_waitcnt lgkmcnt(8)
	v_mfma_f32_16x16x32_bf16 v[42:45], v[182:185], v[154:157], v[42:45]
	v_mfma_f32_16x16x32_bf16 v[46:49], v[182:185], v[158:161], v[46:49]
	s_waitcnt vmcnt(6)
	ds_write_b128 v146, v[98:101] offset:18448
	ds_write_b128 v146, v[102:105] offset:55312
	v_mfma_f32_16x16x32_bf16 v[10:13], v[182:185], v[162:165], v[10:13]
	v_mfma_f32_16x16x32_bf16 v[14:17], v[182:185], v[166:169], v[14:17]
	s_waitcnt lgkmcnt(8)
	v_mfma_f32_16x16x32_bf16 v[50:53], v[214:217], v[198:201], v[50:53]
	s_waitcnt lgkmcnt(7)
	v_mfma_f32_16x16x32_bf16 v[54:57], v[214:217], v[202:205], v[54:57]
	s_waitcnt vmcnt(4)
	ds_write_b128 v146, v[106:109] offset:23056
	ds_write_b128 v146, v[110:113] offset:59920
	s_waitcnt lgkmcnt(8)
	v_mfma_f32_16x16x32_bf16 v[58:61], v[218:221], v[198:201], v[58:61]
	v_mfma_f32_16x16x32_bf16 v[62:65], v[218:221], v[202:205], v[62:65]
	s_waitcnt lgkmcnt(7)
	v_mfma_f32_16x16x32_bf16 v[18:21], v[214:217], v[206:209], v[18:21]
	v_mfma_f32_16x16x32_bf16 v[26:29], v[218:221], v[206:209], v[26:29]
	s_waitcnt vmcnt(2)
	ds_write_b128 v146, v[114:117] offset:27664
	ds_write_b128 v146, v[118:121] offset:64528
	s_waitcnt lgkmcnt(8)
	v_mfma_f32_16x16x32_bf16 v[22:25], v[214:217], v[210:213], v[22:25]
	v_mfma_f32_16x16x32_bf16 v[30:33], v[218:221], v[210:213], v[30:33]
	s_waitcnt lgkmcnt(7)
	v_mfma_f32_16x16x32_bf16 v[34:37], v[222:225], v[198:201], v[34:37]
	v_mfma_f32_16x16x32_bf16 v[38:41], v[222:225], v[202:205], v[38:41]
	s_waitcnt vmcnt(0)
	ds_write_b128 v146, v[122:125] offset:32272
	ds_write_b128 v147, v[126:129] offset:32256
	v_mfma_f32_16x16x32_bf16 v[2:5], v[222:225], v[206:209], v[2:5]
	v_mfma_f32_16x16x32_bf16 v[6:9], v[222:225], v[210:213], v[6:9]
	s_waitcnt lgkmcnt(8)
	v_mfma_f32_16x16x32_bf16 v[42:45], v[226:229], v[198:201], v[42:45]
	v_mfma_f32_16x16x32_bf16 v[46:49], v[226:229], v[202:205], v[46:49]
	v_mfma_f32_16x16x32_bf16 v[10:13], v[226:229], v[206:209], v[10:13]
	v_mfma_f32_16x16x32_bf16 v[14:17], v[226:229], v[210:213], v[14:17]
	s_waitcnt lgkmcnt(0)
	s_barrier
; #define MFMA(a, b, c) __builtin_amdgcn_mfma_f32_32x32x16_bf16((a), (b), (c), 0, 0, 0)
; template <bool SWAP, class Epi>
; DI void gemm_tile(const u16* __restrict__ A, int lda, const u16* __restrict__ Bt, int ldb, int K, int m0, int n0, char* smem, Epi&& epi) {
;     ...
;   auto compute = [&](int buf) __attribute__((always_inline)) {
;     bf16x8 af[2][2], bfr[2][2];
;     af[0][0] = *(const bf16x8*)(Asb + buf * 128 * 72);
;     af[0][1] = *(const bf16x8*)(Asb + buf * 128 * 72 + 32 * 72);
;     bfr[0][0] = *(const bf16x8*)(Bsb + buf * 128 * 72);
;     bfr[0][1] = *(const bf16x8*)(Bsb + buf * 128 * 72 + 32 * 72);
; #pragma unroll
;     for (int ks = 0; ks < 4; ++ks) {
;       const int c = ks & 1, n = c ^ 1;
;       if (ks < 3) {
;         af[n][0] = *(const bf16x8*)(Asb + buf * 128 * 72 + (ks + 1) * 16);
;         af[n][1] = *(const bf16x8*)(Asb + buf * 128 * 72 + 32 * 72 + (ks + 1) * 16);
;         bfr[n][0] = *(const bf16x8*)(Bsb + buf * 128 * 72 + (ks + 1) * 16);
;         bfr[n][1] = *(const bf16x8*)(Bsb + buf * 128 * 72 + 32 * 72 + (ks + 1) * 16);
;       }
;       __builtin_amdgcn_sched_barrier(0);
; #pragma unroll
;       for (int mi = 0; mi < 2; ++mi)
; #pragma unroll
;         for (int ni = 0; ni < 2; ++ni) {
;           if (SWAP) acc[mi][ni] = MFMA(bfr[c][ni], af[c][mi], acc[mi][ni]);
;           else acc[mi][ni] = MFMA(af[c][mi], bfr[c][ni], acc[mi][ni]);
;         }
;       __builtin_amdgcn_sched_barrier(0);
;     }
;   };
;     ...
;     compute(1);
;     if (kt + 2 < KT) {
; #pragma unroll
;       for (int i = 0; i < 4; ++i) { *(u32x4*)(asw + 32 * i * 72) = ra0[i]; *(u32x4*)(bsw + 32 * i * 72) = rb0[i]; }
;     }
;     __syncthreads();
	ds_read_b128 v[170:173], v150 offset:55312
	ds_read_b128 v[154:157], v149 offset:18448
	ds_read_b128 v[158:161], v149 offset:20752
	ds_read_b128 v[174:177], v150 offset:57616
	ds_read_b128 v[162:165], v149 offset:23056
	ds_read_b128 v[166:169], v149 offset:25360
	ds_read_b128 v[178:181], v150 offset:59920
	ds_read_b128 v[182:185], v150 offset:62224
	s_waitcnt lgkmcnt(6)
	v_mfma_f32_16x16x32_bf16 v[50:53], v[170:173], v[154:157], v[50:53]
	s_waitcnt lgkmcnt(5)
	v_mfma_f32_16x16x32_bf16 v[54:57], v[170:173], v[158:161], v[54:57]
	s_waitcnt lgkmcnt(4)
	v_mfma_f32_16x16x32_bf16 v[58:61], v[174:177], v[154:157], v[58:61]
	v_mfma_f32_16x16x32_bf16 v[62:65], v[174:177], v[158:161], v[62:65]
	ds_read_b128 v[214:217], v150 offset:55376
	ds_read_b128 v[198:201], v149 offset:18512
	ds_read_b128 v[202:205], v149 offset:20816
	ds_read_b128 v[218:221], v150 offset:57680
	s_waitcnt lgkmcnt(7)
	v_mfma_f32_16x16x32_bf16 v[18:21], v[170:173], v[162:165], v[18:21]
	v_mfma_f32_16x16x32_bf16 v[26:29], v[174:177], v[162:165], v[26:29]
	s_waitcnt lgkmcnt(6)
	v_mfma_f32_16x16x32_bf16 v[22:25], v[170:173], v[166:169], v[22:25]
	v_mfma_f32_16x16x32_bf16 v[30:33], v[174:177], v[166:169], v[30:33]
	ds_read_b128 v[206:209], v149 offset:23120
	ds_read_b128 v[210:213], v149 offset:25424
	ds_read_b128 v[222:225], v150 offset:59984
	ds_read_b128 v[226:229], v150 offset:62288
	s_waitcnt lgkmcnt(9)
	v_mfma_f32_16x16x32_bf16 v[34:37], v[178:181], v[154:157], v[34:37]
	v_mfma_f32_16x16x32_bf16 v[38:41], v[178:181], v[158:161], v[38:41]
	v_mfma_f32_16x16x32_bf16 v[2:5], v[178:181], v[162:165], v[2:5]
	v_mfma_f32_16x16x32_bf16 v[6:9], v[178:181], v[166:169], v[6:9]
	s_waitcnt lgkmcnt(8)
	v_mfma_f32_16x16x32_bf16 v[42:45], v[182:185], v[154:157], v[42:45]
	v_mfma_f32_16x16x32_bf16 v[46:49], v[182:185], v[158:161], v[46:49]
	v_mfma_f32_16x16x32_bf16 v[10:13], v[182:185], v[162:165], v[10:13]
	v_mfma_f32_16x16x32_bf16 v[14:17], v[182:185], v[166:169], v[14:17]
	s_waitcnt lgkmcnt(6)
	v_mfma_f32_16x16x32_bf16 v[50:53], v[214:217], v[198:201], v[50:53]
	s_waitcnt lgkmcnt(5)
	v_mfma_f32_16x16x32_bf16 v[54:57], v[214:217], v[202:205], v[54:57]
	s_waitcnt lgkmcnt(4)
	v_mfma_f32_16x16x32_bf16 v[58:61], v[218:221], v[198:201], v[58:61]
	v_mfma_f32_16x16x32_bf16 v[62:65], v[218:221], v[202:205], v[62:65]
	s_waitcnt lgkmcnt(3)
	v_mfma_f32_16x16x32_bf16 v[18:21], v[214:217], v[206:209], v[18:21]
	v_mfma_f32_16x16x32_bf16 v[26:29], v[218:221], v[206:209], v[26:29]
	s_waitcnt lgkmcnt(2)
	v_mfma_f32_16x16x32_bf16 v[22:25], v[214:217], v[210:213], v[22:25]
	v_mfma_f32_16x16x32_bf16 v[30:33], v[218:221], v[210:213], v[30:33]
	s_waitcnt lgkmcnt(1)
	v_mfma_f32_16x16x32_bf16 v[34:37], v[222:225], v[198:201], v[34:37]
	v_mfma_f32_16x16x32_bf16 v[38:41], v[222:225], v[202:205], v[38:41]
	v_mfma_f32_16x16x32_bf16 v[2:5], v[222:225], v[206:209], v[2:5]
	v_mfma_f32_16x16x32_bf16 v[6:9], v[222:225], v[210:213], v[6:9]
	s_waitcnt lgkmcnt(0)
	v_mfma_f32_16x16x32_bf16 v[42:45], v[226:229], v[198:201], v[42:45]
	v_mfma_f32_16x16x32_bf16 v[46:49], v[226:229], v[202:205], v[46:49]
	v_mfma_f32_16x16x32_bf16 v[10:13], v[226:229], v[206:209], v[10:13]
	v_mfma_f32_16x16x32_bf16 v[14:17], v[226:229], v[210:213], v[14:17]
	s_nop 7
	s_nop 7
	v_permlane16_swap_b32_e32 v50, v54
	v_permlane16_swap_b32_e32 v51, v55
	v_permlane16_swap_b32_e32 v52, v56
	v_permlane16_swap_b32_e32 v53, v57
	v_permlane16_swap_b32_e32 v58, v62
	v_permlane16_swap_b32_e32 v59, v63
	v_permlane16_swap_b32_e32 v60, v64
	v_permlane16_swap_b32_e32 v61, v65
	v_permlane16_swap_b32_e32 v34, v38
	v_permlane16_swap_b32_e32 v35, v39
	v_permlane16_swap_b32_e32 v36, v40
	v_permlane16_swap_b32_e32 v37, v41
	v_permlane16_swap_b32_e32 v42, v46
	v_permlane16_swap_b32_e32 v43, v47
	v_permlane16_swap_b32_e32 v44, v48
	v_permlane16_swap_b32_e32 v45, v49
	v_permlane16_swap_b32_e32 v18, v22
	v_permlane16_swap_b32_e32 v19, v23
	v_permlane16_swap_b32_e32 v20, v24
	v_permlane16_swap_b32_e32 v21, v25
	v_permlane16_swap_b32_e32 v26, v30
	v_permlane16_swap_b32_e32 v27, v31
	v_permlane16_swap_b32_e32 v28, v32
	v_permlane16_swap_b32_e32 v29, v33
	v_permlane16_swap_b32_e32 v2, v6
	v_permlane16_swap_b32_e32 v3, v7
	v_permlane16_swap_b32_e32 v4, v8
	v_permlane16_swap_b32_e32 v5, v9
	v_permlane16_swap_b32_e32 v10, v14
	v_permlane16_swap_b32_e32 v11, v15
	v_permlane16_swap_b32_e32 v12, v16
	v_permlane16_swap_b32_e32 v13, v17
	v_permlane32_swap_b32_e32 v50, v54
	v_permlane32_swap_b32_e32 v51, v55
	v_permlane32_swap_b32_e32 v52, v56
	v_permlane32_swap_b32_e32 v53, v57
	v_permlane32_swap_b32_e32 v58, v62
	v_permlane32_swap_b32_e32 v59, v63
	v_permlane32_swap_b32_e32 v60, v64
	v_permlane32_swap_b32_e32 v61, v65
	v_permlane32_swap_b32_e32 v34, v38
	v_permlane32_swap_b32_e32 v35, v39
	v_permlane32_swap_b32_e32 v36, v40
	v_permlane32_swap_b32_e32 v37, v41
	v_permlane32_swap_b32_e32 v42, v46
	v_permlane32_swap_b32_e32 v43, v47
	v_permlane32_swap_b32_e32 v44, v48
	v_permlane32_swap_b32_e32 v45, v49
	v_permlane32_swap_b32_e32 v18, v22
	v_permlane32_swap_b32_e32 v19, v23
	v_permlane32_swap_b32_e32 v20, v24
	v_permlane32_swap_b32_e32 v21, v25
	v_permlane32_swap_b32_e32 v26, v30
	v_permlane32_swap_b32_e32 v27, v31
	v_permlane32_swap_b32_e32 v28, v32
	v_permlane32_swap_b32_e32 v29, v33
	v_permlane32_swap_b32_e32 v2, v6
	v_permlane32_swap_b32_e32 v3, v7
	v_permlane32_swap_b32_e32 v4, v8
	v_permlane32_swap_b32_e32 v5, v9
	v_permlane32_swap_b32_e32 v10, v14
	v_permlane32_swap_b32_e32 v11, v15
	v_permlane32_swap_b32_e32 v12, v16
	v_permlane32_swap_b32_e32 v13, v17
	s_waitcnt lgkmcnt(0)
	s_barrier
	s_branch .LBB0_393

; #define MFMA(a, b, c) __builtin_amdgcn_mfma_f32_32x32x16_bf16((a), (b), (c), 0, 0, 0)
; template <bool SWAP, class Epi>
; DI void gemm_tile(const u16* __restrict__ A, int lda, const u16* __restrict__ Bt, int ldb, int K, int m0, int n0, char* smem, Epi&& epi) {
;     ...
;   auto compute = [&](int buf) __attribute__((always_inline)) {
;     bf16x8 af[2][2], bfr[2][2];
;     af[0][0] = *(const bf16x8*)(Asb + buf * 128 * 72);
;     af[0][1] = *(const bf16x8*)(Asb + buf * 128 * 72 + 32 * 72);
;     bfr[0][0] = *(const bf16x8*)(Bsb + buf * 128 * 72);
;     bfr[0][1] = *(const bf16x8*)(Bsb + buf * 128 * 72 + 32 * 72);
; #pragma unroll
;     for (int ks = 0; ks < 4; ++ks) {
;       const int c = ks & 1, n = c ^ 1;
;       if (ks < 3) {
;         af[n][0] = *(const bf16x8*)(Asb + buf * 128 * 72 + (ks + 1) * 16);
;         af[n][1] = *(const bf16x8*)(Asb + buf * 128 * 72 + 32 * 72 + (ks + 1) * 16);
;         bfr[n][0] = *(const bf16x8*)(Bsb + buf * 128 * 72 + (ks + 1) * 16);
;         bfr[n][1] = *(const bf16x8*)(Bsb + buf * 128 * 72 + 32 * 72 + (ks + 1) * 16);
;       }
;       __builtin_amdgcn_sched_barrier(0);
; #pragma unroll
;       for (int mi = 0; mi < 2; ++mi)
; #pragma unroll
;         for (int ni = 0; ni < 2; ++ni) {
;           if (SWAP) acc[mi][ni] = MFMA(bfr[c][ni], af[c][mi], acc[mi][ni]);
;           else acc[mi][ni] = MFMA(af[c][mi], bfr[c][ni], acc[mi][ni]);
;         }
;       __builtin_amdgcn_sched_barrier(0);
;     }
;   };
;   for (int kt = 0; kt < KT; kt += 2) {
;     if (kt + 2 < KT) {
;       const int k0 = (kt + 2) << 6;
; #pragma unroll
;       for (int i = 0; i < 4; ++i) { ra0[i] = *(const u32x4*)(ag + (size_t)i * 32 * lda + k0); rb0[i] = *(const u32x4*)(bg + (size_t)i * 32 * ldb + k0); }
;     }
;     compute(0);
; #pragma unroll
;     for (int i = 0; i < 4; ++i) { *(u32x4*)(asw + 128 * 72 + 32 * i * 72) = ra1[i]; *(u32x4*)(bsw + 128 * 72 + 32 * i * 72) = rb1[i]; }
;     __syncthreads();
;     if (kt + 3 < KT) {
;       const int k0 = (kt + 3) << 6;
; #pragma unroll
;       for (int i = 0; i < 4; ++i) { ra1[i] = *(const u32x4*)(ag + (size_t)i * 32 * lda + k0); rb1[i] = *(const u32x4*)(bg + (size_t)i * 32 * ldb + k0); }
;     }
;     compute(1);
.LBB0_748:
	global_load_dwordx4 v[66:69], v194, s[100:101] offset:256
	global_load_dwordx4 v[70:73], v190, s[98:99] offset:256
	global_load_dwordx4 v[74:77], v195, s[100:101] offset:256
	global_load_dwordx4 v[78:81], v191, s[98:99] offset:256
	global_load_dwordx4 v[82:85], v196, s[100:101] offset:256
	global_load_dwordx4 v[86:89], v192, s[98:99] offset:256
	global_load_dwordx4 v[90:93], v197, s[100:101] offset:256
	global_load_dwordx4 v[94:97], v193, s[98:99] offset:256
	ds_read_b128 v[166:169], v148 offset:36880
	ds_read_b128 v[150:153], v147 offset:16
	ds_read_b128 v[154:157], v147 offset:2320
	ds_read_b128 v[170:173], v148 offset:39184
	ds_read_b128 v[158:161], v147 offset:4624
	ds_read_b128 v[162:165], v147 offset:6928
	ds_read_b128 v[174:177], v148 offset:41488
	ds_read_b128 v[178:181], v148 offset:43792
	s_waitcnt lgkmcnt(6)
	v_mfma_f32_16x16x32_bf16 v[50:53], v[166:169], v[150:153], v[50:53]
	s_waitcnt lgkmcnt(5)
	v_mfma_f32_16x16x32_bf16 v[54:57], v[166:169], v[154:157], v[54:57]
	s_waitcnt lgkmcnt(4)
	v_mfma_f32_16x16x32_bf16 v[58:61], v[170:173], v[150:153], v[58:61]
	v_mfma_f32_16x16x32_bf16 v[62:65], v[170:173], v[154:157], v[62:65]
	ds_read_b128 v[214:217], v148 offset:36944
	ds_read_b128 v[198:201], v147 offset:80
	ds_read_b128 v[202:205], v147 offset:2384
	ds_read_b128 v[218:221], v148 offset:39248
	s_waitcnt lgkmcnt(7)
	v_mfma_f32_16x16x32_bf16 v[18:21], v[166:169], v[158:161], v[18:21]
	v_mfma_f32_16x16x32_bf16 v[26:29], v[170:173], v[158:161], v[26:29]
	s_waitcnt lgkmcnt(6)
	v_mfma_f32_16x16x32_bf16 v[22:25], v[166:169], v[162:165], v[22:25]
	v_mfma_f32_16x16x32_bf16 v[30:33], v[170:173], v[162:165], v[30:33]
	ds_read_b128 v[206:209], v147 offset:4688
	ds_read_b128 v[210:213], v147 offset:6992
	ds_read_b128 v[222:225], v148 offset:41552
	ds_read_b128 v[226:229], v148 offset:43856
	s_waitcnt lgkmcnt(9)
	v_mfma_f32_16x16x32_bf16 v[34:37], v[174:177], v[150:153], v[34:37]
	v_mfma_f32_16x16x32_bf16 v[38:41], v[174:177], v[154:157], v[38:41]
	v_mfma_f32_16x16x32_bf16 v[2:5], v[174:177], v[158:161], v[2:5]
	v_mfma_f32_16x16x32_bf16 v[6:9], v[174:177], v[162:165], v[6:9]
	s_waitcnt lgkmcnt(8)
	v_mfma_f32_16x16x32_bf16 v[42:45], v[178:181], v[150:153], v[42:45]
	v_mfma_f32_16x16x32_bf16 v[46:49], v[178:181], v[154:157], v[46:49]
	s_waitcnt vmcnt(14)
	ds_write_b128 v144, v[98:101] offset:18448
	ds_write_b128 v144, v[102:105] offset:55312
	v_mfma_f32_16x16x32_bf16 v[10:13], v[178:181], v[158:161], v[10:13]
	v_mfma_f32_16x16x32_bf16 v[14:17], v[178:181], v[162:165], v[14:17]
	s_waitcnt lgkmcnt(8)
	v_mfma_f32_16x16x32_bf16 v[50:53], v[214:217], v[198:201], v[50:53]
	s_waitcnt lgkmcnt(7)
	v_mfma_f32_16x16x32_bf16 v[54:57], v[214:217], v[202:205], v[54:57]
	s_waitcnt vmcnt(12)
	ds_write_b128 v144, v[106:109] offset:23056
	ds_write_b128 v144, v[110:113] offset:59920
	s_waitcnt lgkmcnt(8)
	v_mfma_f32_16x16x32_bf16 v[58:61], v[218:221], v[198:201], v[58:61]
	v_mfma_f32_16x16x32_bf16 v[62:65], v[218:221], v[202:205], v[62:65]
	s_waitcnt lgkmcnt(7)
	v_mfma_f32_16x16x32_bf16 v[18:21], v[214:217], v[206:209], v[18:21]
	v_mfma_f32_16x16x32_bf16 v[26:29], v[218:221], v[206:209], v[26:29]
	s_waitcnt vmcnt(10)
	ds_write_b128 v144, v[114:117] offset:27664
	ds_write_b128 v144, v[118:121] offset:64528
	s_waitcnt lgkmcnt(8)
	v_mfma_f32_16x16x32_bf16 v[22:25], v[214:217], v[210:213], v[22:25]
	v_mfma_f32_16x16x32_bf16 v[30:33], v[218:221], v[210:213], v[30:33]
	s_waitcnt lgkmcnt(7)
	v_mfma_f32_16x16x32_bf16 v[34:37], v[222:225], v[198:201], v[34:37]
	v_mfma_f32_16x16x32_bf16 v[38:41], v[222:225], v[202:205], v[38:41]
	s_waitcnt vmcnt(8)
	ds_write_b128 v144, v[122:125] offset:32272
	ds_write_b128 v145, v[126:129] offset:32256
	v_mfma_f32_16x16x32_bf16 v[2:5], v[222:225], v[206:209], v[2:5]
	v_mfma_f32_16x16x32_bf16 v[6:9], v[222:225], v[210:213], v[6:9]
	s_waitcnt lgkmcnt(8)
	v_mfma_f32_16x16x32_bf16 v[42:45], v[226:229], v[198:201], v[42:45]
	v_mfma_f32_16x16x32_bf16 v[46:49], v[226:229], v[202:205], v[46:49]
	v_mfma_f32_16x16x32_bf16 v[10:13], v[226:229], v[206:209], v[10:13]
	v_mfma_f32_16x16x32_bf16 v[14:17], v[226:229], v[210:213], v[14:17]
	s_waitcnt lgkmcnt(0)
	s_barrier
	global_load_dwordx4 v[98:101], v194, s[100:101] offset:384
	global_load_dwordx4 v[102:105], v190, s[98:99] offset:384
	global_load_dwordx4 v[106:109], v195, s[100:101] offset:384
	global_load_dwordx4 v[110:113], v191, s[98:99] offset:384
	global_load_dwordx4 v[114:117], v196, s[100:101] offset:384
	global_load_dwordx4 v[118:121], v192, s[98:99] offset:384
	global_load_dwordx4 v[122:125], v197, s[100:101] offset:384
	global_load_dwordx4 v[126:129], v193, s[98:99] offset:384
	ds_read_b128 v[166:169], v148 offset:55312
	ds_read_b128 v[150:153], v147 offset:18448
	ds_read_b128 v[154:157], v147 offset:20752
	ds_read_b128 v[170:173], v148 offset:57616
	ds_read_b128 v[158:161], v147 offset:23056
	ds_read_b128 v[162:165], v147 offset:25360
	ds_read_b128 v[174:177], v148 offset:59920
	ds_read_b128 v[178:181], v148 offset:62224
	s_waitcnt lgkmcnt(6)
	v_mfma_f32_16x16x32_bf16 v[50:53], v[166:169], v[150:153], v[50:53]
	s_waitcnt lgkmcnt(5)
	v_mfma_f32_16x16x32_bf16 v[54:57], v[166:169], v[154:157], v[54:57]
	s_waitcnt lgkmcnt(4)
	v_mfma_f32_16x16x32_bf16 v[58:61], v[170:173], v[150:153], v[58:61]
	v_mfma_f32_16x16x32_bf16 v[62:65], v[170:173], v[154:157], v[62:65]
	ds_read_b128 v[214:217], v148 offset:55376
	ds_read_b128 v[198:201], v147 offset:18512
	ds_read_b128 v[202:205], v147 offset:20816
	ds_read_b128 v[218:221], v148 offset:57680
	s_waitcnt lgkmcnt(7)
	v_mfma_f32_16x16x32_bf16 v[18:21], v[166:169], v[158:161], v[18:21]
	v_mfma_f32_16x16x32_bf16 v[26:29], v[170:173], v[158:161], v[26:29]
	s_waitcnt lgkmcnt(6)
; #define MFMA(a, b, c) __builtin_amdgcn_mfma_f32_32x32x16_bf16((a), (b), (c), 0, 0, 0)
; template <bool SWAP, class Epi>
; DI void gemm_tile(const u16* __restrict__ A, int lda, const u16* __restrict__ Bt, int ldb, int K, int m0, int n0, char* smem, Epi&& epi) {
;     ...
;   auto compute = [&](int buf) __attribute__((always_inline)) {
;     bf16x8 af[2][2], bfr[2][2];
;     af[0][0] = *(const bf16x8*)(Asb + buf * 128 * 72);
;     af[0][1] = *(const bf16x8*)(Asb + buf * 128 * 72 + 32 * 72);
;     bfr[0][0] = *(const bf16x8*)(Bsb + buf * 128 * 72);
;     bfr[0][1] = *(const bf16x8*)(Bsb + buf * 128 * 72 + 32 * 72);
; #pragma unroll
;     for (int ks = 0; ks < 4; ++ks) {
;       const int c = ks & 1, n = c ^ 1;
;       if (ks < 3) {
;         af[n][0] = *(const bf16x8*)(Asb + buf * 128 * 72 + (ks + 1) * 16);
;         af[n][1] = *(const bf16x8*)(Asb + buf * 128 * 72 + 32 * 72 + (ks + 1) * 16);
;         bfr[n][0] = *(const bf16x8*)(Bsb + buf * 128 * 72 + (ks + 1) * 16);
;         bfr[n][1] = *(const bf16x8*)(Bsb + buf * 128 * 72 + 32 * 72 + (ks + 1) * 16);
;       }
;       __builtin_amdgcn_sched_barrier(0);
; #pragma unroll
;       for (int mi = 0; mi < 2; ++mi)
; #pragma unroll
;         for (int ni = 0; ni < 2; ++ni) {
;           if (SWAP) acc[mi][ni] = MFMA(bfr[c][ni], af[c][mi], acc[mi][ni]);
;           else acc[mi][ni] = MFMA(af[c][mi], bfr[c][ni], acc[mi][ni]);
;         }
;       __builtin_amdgcn_sched_barrier(0);
;     }
;   };
;   for (int kt = 0; kt < KT; kt += 2) {
;     if (kt + 2 < KT) {
;       const int k0 = (kt + 2) << 6;
; #pragma unroll
;       for (int i = 0; i < 4; ++i) { ra0[i] = *(const u32x4*)(ag + (size_t)i * 32 * lda + k0); rb0[i] = *(const u32x4*)(bg + (size_t)i * 32 * ldb + k0); }
;     }
;     compute(0);
; #pragma unroll
;     for (int i = 0; i < 4; ++i) { *(u32x4*)(asw + 128 * 72 + 32 * i * 72) = ra1[i]; *(u32x4*)(bsw + 128 * 72 + 32 * i * 72) = rb1[i]; }
;     __syncthreads();
;     if (kt + 3 < KT) {
;       const int k0 = (kt + 3) << 6;
; #pragma unroll
;       for (int i = 0; i < 4; ++i) { ra1[i] = *(const u32x4*)(ag + (size_t)i * 32 * lda + k0); rb1[i] = *(const u32x4*)(bg + (size_t)i * 32 * ldb + k0); }
;     }
;     compute(1);
;     if (kt + 2 < KT) {
; #pragma unroll
;       for (int i = 0; i < 4; ++i) { *(u32x4*)(asw + 32 * i * 72) = ra0[i]; *(u32x4*)(bsw + 32 * i * 72) = rb0[i]; }
;     }
;     __syncthreads();
;   }
	v_mfma_f32_16x16x32_bf16 v[22:25], v[166:169], v[162:165], v[22:25]
	v_mfma_f32_16x16x32_bf16 v[30:33], v[170:173], v[162:165], v[30:33]
	ds_read_b128 v[206:209], v147 offset:23120
	ds_read_b128 v[210:213], v147 offset:25424
	ds_read_b128 v[222:225], v148 offset:59984
	ds_read_b128 v[226:229], v148 offset:62288
	s_waitcnt lgkmcnt(9)
	v_mfma_f32_16x16x32_bf16 v[34:37], v[174:177], v[150:153], v[34:37]
	v_mfma_f32_16x16x32_bf16 v[38:41], v[174:177], v[154:157], v[38:41]
	v_mfma_f32_16x16x32_bf16 v[2:5], v[174:177], v[158:161], v[2:5]
	v_mfma_f32_16x16x32_bf16 v[6:9], v[174:177], v[162:165], v[6:9]
	s_waitcnt lgkmcnt(8)
	v_mfma_f32_16x16x32_bf16 v[42:45], v[178:181], v[150:153], v[42:45]
	v_mfma_f32_16x16x32_bf16 v[46:49], v[178:181], v[154:157], v[46:49]
	s_waitcnt vmcnt(14)
	ds_write_b128 v144, v[66:69] offset:16
	ds_write_b128 v144, v[70:73] offset:36880
	v_mfma_f32_16x16x32_bf16 v[10:13], v[178:181], v[158:161], v[10:13]
	v_mfma_f32_16x16x32_bf16 v[14:17], v[178:181], v[162:165], v[14:17]
	s_waitcnt lgkmcnt(8)
	v_mfma_f32_16x16x32_bf16 v[50:53], v[214:217], v[198:201], v[50:53]
	s_waitcnt lgkmcnt(7)
	v_mfma_f32_16x16x32_bf16 v[54:57], v[214:217], v[202:205], v[54:57]
	s_waitcnt vmcnt(12)
	ds_write_b128 v144, v[74:77] offset:4624
	ds_write_b128 v144, v[78:81] offset:41488
	s_waitcnt lgkmcnt(8)
	v_mfma_f32_16x16x32_bf16 v[58:61], v[218:221], v[198:201], v[58:61]
	v_mfma_f32_16x16x32_bf16 v[62:65], v[218:221], v[202:205], v[62:65]
	s_waitcnt lgkmcnt(7)
	v_mfma_f32_16x16x32_bf16 v[18:21], v[214:217], v[206:209], v[18:21]
	v_mfma_f32_16x16x32_bf16 v[26:29], v[218:221], v[206:209], v[26:29]
	s_waitcnt vmcnt(10)
	ds_write_b128 v144, v[82:85] offset:9232
	ds_write_b128 v144, v[86:89] offset:46096
	s_waitcnt lgkmcnt(8)
	v_mfma_f32_16x16x32_bf16 v[22:25], v[214:217], v[210:213], v[22:25]
	v_mfma_f32_16x16x32_bf16 v[30:33], v[218:221], v[210:213], v[30:33]
	s_waitcnt lgkmcnt(7)
	v_mfma_f32_16x16x32_bf16 v[34:37], v[222:225], v[198:201], v[34:37]
	v_mfma_f32_16x16x32_bf16 v[38:41], v[222:225], v[202:205], v[38:41]
	s_waitcnt vmcnt(8)
	ds_write_b128 v144, v[90:93] offset:13840
	ds_write_b128 v144, v[94:97] offset:50704
	v_mfma_f32_16x16x32_bf16 v[2:5], v[222:225], v[206:209], v[2:5]
	v_mfma_f32_16x16x32_bf16 v[6:9], v[222:225], v[210:213], v[6:9]
	s_waitcnt lgkmcnt(8)
	v_mfma_f32_16x16x32_bf16 v[42:45], v[226:229], v[198:201], v[42:45]
	v_mfma_f32_16x16x32_bf16 v[46:49], v[226:229], v[202:205], v[46:49]
	v_mfma_f32_16x16x32_bf16 v[10:13], v[226:229], v[206:209], v[10:13]
	v_mfma_f32_16x16x32_bf16 v[14:17], v[226:229], v[210:213], v[14:17]
	s_add_i32 s20, s20, 2
	s_add_u32 s98, s98, 256
	s_addc_u32 s99, s99, 0
	s_add_u32 s100, s100, 256
	s_addc_u32 s101, s101, 0
	s_waitcnt lgkmcnt(0)
	s_barrier
	s_cmp_lt_u32 s20, 30
	s_cbranch_scc1 .LBB0_748
	ds_read_b128 v[166:169], v148 offset:36880
	ds_read_b128 v[150:153], v147 offset:16
	ds_read_b128 v[154:157], v147 offset:2320
	ds_read_b128 v[170:173], v148 offset:39184
	ds_read_b128 v[158:161], v147 offset:4624
	ds_read_b128 v[162:165], v147 offset:6928
	ds_read_b128 v[174:177], v148 offset:41488
	ds_read_b128 v[178:181], v148 offset:43792
	s_waitcnt lgkmcnt(6)
	v_mfma_f32_16x16x32_bf16 v[50:53], v[166:169], v[150:153], v[50:53]
	s_waitcnt lgkmcnt(5)
	v_mfma_f32_16x16x32_bf16 v[54:57], v[166:169], v[154:157], v[54:57]
	s_waitcnt lgkmcnt(4)
	v_mfma_f32_16x16x32_bf16 v[58:61], v[170:173], v[150:153], v[58:61]
	v_mfma_f32_16x16x32_bf16 v[62:65], v[170:173], v[154:157], v[62:65]
	ds_read_b128 v[214:217], v148 offset:36944
	ds_read_b128 v[198:201], v147 offset:80
	ds_read_b128 v[202:205], v147 offset:2384
	ds_read_b128 v[218:221], v148 offset:39248
	s_waitcnt lgkmcnt(7)
	v_mfma_f32_16x16x32_bf16 v[18:21], v[166:169], v[158:161], v[18:21]
	v_mfma_f32_16x16x32_bf16 v[26:29], v[170:173], v[158:161], v[26:29]
	s_waitcnt lgkmcnt(6)
	v_mfma_f32_16x16x32_bf16 v[22:25], v[166:169], v[162:165], v[22:25]
	v_mfma_f32_16x16x32_bf16 v[30:33], v[170:173], v[162:165], v[30:33]
	ds_read_b128 v[206:209], v147 offset:4688
	ds_read_b128 v[210:213], v147 offset:6992
	ds_read_b128 v[222:225], v148 offset:41552
	ds_read_b128 v[226:229], v148 offset:43856
	s_waitcnt lgkmcnt(9)
	v_mfma_f32_16x16x32_bf16 v[34:37], v[174:177], v[150:153], v[34:37]
	v_mfma_f32_16x16x32_bf16 v[38:41], v[174:177], v[154:157], v[38:41]
	v_mfma_f32_16x16x32_bf16 v[2:5], v[174:177], v[158:161], v[2:5]
	v_mfma_f32_16x16x32_bf16 v[6:9], v[174:177], v[162:165], v[6:9]
	s_waitcnt lgkmcnt(8)
	v_mfma_f32_16x16x32_bf16 v[42:45], v[178:181], v[150:153], v[42:45]
	v_mfma_f32_16x16x32_bf16 v[46:49], v[178:181], v[154:157], v[46:49]
	s_waitcnt vmcnt(6)
	ds_write_b128 v144, v[98:101] offset:18448
	ds_write_b128 v144, v[102:105] offset:55312
	v_mfma_f32_16x16x32_bf16 v[10:13], v[178:181], v[158:161], v[10:13]
	v_mfma_f32_16x16x32_bf16 v[14:17], v[178:181], v[162:165], v[14:17]
	s_waitcnt lgkmcnt(8)
	v_mfma_f32_16x16x32_bf16 v[50:53], v[214:217], v[198:201], v[50:53]
	s_waitcnt lgkmcnt(7)
	v_mfma_f32_16x16x32_bf16 v[54:57], v[214:217], v[202:205], v[54:57]
	s_waitcnt vmcnt(4)
	ds_write_b128 v144, v[106:109] offset:23056
	ds_write_b128 v144, v[110:113] offset:59920
	s_waitcnt lgkmcnt(8)
	v_mfma_f32_16x16x32_bf16 v[58:61], v[218:221], v[198:201], v[58:61]
	v_mfma_f32_16x16x32_bf16 v[62:65], v[218:221], v[202:205], v[62:65]
	s_waitcnt lgkmcnt(7)
	v_mfma_f32_16x16x32_bf16 v[18:21], v[214:217], v[206:209], v[18:21]
	v_mfma_f32_16x16x32_bf16 v[26:29], v[218:221], v[206:209], v[26:29]
	s_waitcnt vmcnt(2)
	ds_write_b128 v144, v[114:117] offset:27664
	ds_write_b128 v144, v[118:121] offset:64528
	s_waitcnt lgkmcnt(8)
	v_mfma_f32_16x16x32_bf16 v[22:25], v[214:217], v[210:213], v[22:25]
	v_mfma_f32_16x16x32_bf16 v[30:33], v[218:221], v[210:213], v[30:33]
	s_waitcnt lgkmcnt(7)
	v_mfma_f32_16x16x32_bf16 v[34:37], v[222:225], v[198:201], v[34:37]
	v_mfma_f32_16x16x32_bf16 v[38:41], v[222:225], v[202:205], v[38:41]
	s_waitcnt vmcnt(0)
	ds_write_b128 v144, v[122:125] offset:32272
	ds_write_b128 v145, v[126:129] offset:32256
	v_mfma_f32_16x16x32_bf16 v[2:5], v[222:225], v[206:209], v[2:5]
	v_mfma_f32_16x16x32_bf16 v[6:9], v[222:225], v[210:213], v[6:9]
	s_waitcnt lgkmcnt(8)
	v_mfma_f32_16x16x32_bf16 v[42:45], v[226:229], v[198:201], v[42:45]
	v_mfma_f32_16x16x32_bf16 v[46:49], v[226:229], v[202:205], v[46:49]
	v_mfma_f32_16x16x32_bf16 v[10:13], v[226:229], v[206:209], v[10:13]
	v_mfma_f32_16x16x32_bf16 v[14:17], v[226:229], v[210:213], v[14:17]
	s_waitcnt lgkmcnt(0)
	s_barrier
; #define MFMA(a, b, c) __builtin_amdgcn_mfma_f32_32x32x16_bf16((a), (b), (c), 0, 0, 0)
; template <bool SWAP, class Epi>
; DI void gemm_tile(const u16* __restrict__ A, int lda, const u16* __restrict__ Bt, int ldb, int K, int m0, int n0, char* smem, Epi&& epi) {
;     ...
;   auto compute = [&](int buf) __attribute__((always_inline)) {
;     bf16x8 af[2][2], bfr[2][2];
;     af[0][0] = *(const bf16x8*)(Asb + buf * 128 * 72);
;     af[0][1] = *(const bf16x8*)(Asb + buf * 128 * 72 + 32 * 72);
;     bfr[0][0] = *(const bf16x8*)(Bsb + buf * 128 * 72);
;     bfr[0][1] = *(const bf16x8*)(Bsb + buf * 128 * 72 + 32 * 72);
; #pragma unroll
;     for (int ks = 0; ks < 4; ++ks) {
;       const int c = ks & 1, n = c ^ 1;
;       if (ks < 3) {
;         af[n][0] = *(const bf16x8*)(Asb + buf * 128 * 72 + (ks + 1) * 16);
;         af[n][1] = *(const bf16x8*)(Asb + buf * 128 * 72 + 32 * 72 + (ks + 1) * 16);
;         bfr[n][0] = *(const bf16x8*)(Bsb + buf * 128 * 72 + (ks + 1) * 16);
;         bfr[n][1] = *(const bf16x8*)(Bsb + buf * 128 * 72 + 32 * 72 + (ks + 1) * 16);
;       }
;       __builtin_amdgcn_sched_barrier(0);
; #pragma unroll
;       for (int mi = 0; mi < 2; ++mi)
; #pragma unroll
;         for (int ni = 0; ni < 2; ++ni) {
;           if (SWAP) acc[mi][ni] = MFMA(bfr[c][ni], af[c][mi], acc[mi][ni]);
;           else acc[mi][ni] = MFMA(af[c][mi], bfr[c][ni], acc[mi][ni]);
;         }
;       __builtin_amdgcn_sched_barrier(0);
;     }
;   };
;     ...
;     compute(1);
;     if (kt + 2 < KT) {
; #pragma unroll
;       for (int i = 0; i < 4; ++i) { *(u32x4*)(asw + 32 * i * 72) = ra0[i]; *(u32x4*)(bsw + 32 * i * 72) = rb0[i]; }
;     }
;     __syncthreads();
	ds_read_b128 v[166:169], v148 offset:55312
	ds_read_b128 v[150:153], v147 offset:18448
	ds_read_b128 v[154:157], v147 offset:20752
	ds_read_b128 v[170:173], v148 offset:57616
	ds_read_b128 v[158:161], v147 offset:23056
	ds_read_b128 v[162:165], v147 offset:25360
	ds_read_b128 v[174:177], v148 offset:59920
	ds_read_b128 v[178:181], v148 offset:62224
	s_waitcnt lgkmcnt(6)
	v_mfma_f32_16x16x32_bf16 v[50:53], v[166:169], v[150:153], v[50:53]
	s_waitcnt lgkmcnt(5)
	v_mfma_f32_16x16x32_bf16 v[54:57], v[166:169], v[154:157], v[54:57]
	s_waitcnt lgkmcnt(4)
	v_mfma_f32_16x16x32_bf16 v[58:61], v[170:173], v[150:153], v[58:61]
	v_mfma_f32_16x16x32_bf16 v[62:65], v[170:173], v[154:157], v[62:65]
	ds_read_b128 v[214:217], v148 offset:55376
	ds_read_b128 v[198:201], v147 offset:18512
	ds_read_b128 v[202:205], v147 offset:20816
	ds_read_b128 v[218:221], v148 offset:57680
	s_waitcnt lgkmcnt(7)
	v_mfma_f32_16x16x32_bf16 v[18:21], v[166:169], v[158:161], v[18:21]
	v_mfma_f32_16x16x32_bf16 v[26:29], v[170:173], v[158:161], v[26:29]
	s_waitcnt lgkmcnt(6)
	v_mfma_f32_16x16x32_bf16 v[22:25], v[166:169], v[162:165], v[22:25]
	v_mfma_f32_16x16x32_bf16 v[30:33], v[170:173], v[162:165], v[30:33]
	ds_read_b128 v[206:209], v147 offset:23120
	ds_read_b128 v[210:213], v147 offset:25424
	ds_read_b128 v[222:225], v148 offset:59984
	ds_read_b128 v[226:229], v148 offset:62288
	s_waitcnt lgkmcnt(9)
	v_mfma_f32_16x16x32_bf16 v[34:37], v[174:177], v[150:153], v[34:37]
	v_mfma_f32_16x16x32_bf16 v[38:41], v[174:177], v[154:157], v[38:41]
	v_mfma_f32_16x16x32_bf16 v[2:5], v[174:177], v[158:161], v[2:5]
	v_mfma_f32_16x16x32_bf16 v[6:9], v[174:177], v[162:165], v[6:9]
	s_waitcnt lgkmcnt(8)
	v_mfma_f32_16x16x32_bf16 v[42:45], v[178:181], v[150:153], v[42:45]
	v_mfma_f32_16x16x32_bf16 v[46:49], v[178:181], v[154:157], v[46:49]
	v_mfma_f32_16x16x32_bf16 v[10:13], v[178:181], v[158:161], v[10:13]
	v_mfma_f32_16x16x32_bf16 v[14:17], v[178:181], v[162:165], v[14:17]
	s_waitcnt lgkmcnt(6)
	v_mfma_f32_16x16x32_bf16 v[50:53], v[214:217], v[198:201], v[50:53]
	s_waitcnt lgkmcnt(5)
	v_mfma_f32_16x16x32_bf16 v[54:57], v[214:217], v[202:205], v[54:57]
	s_waitcnt lgkmcnt(4)
	v_mfma_f32_16x16x32_bf16 v[58:61], v[218:221], v[198:201], v[58:61]
	v_mfma_f32_16x16x32_bf16 v[62:65], v[218:221], v[202:205], v[62:65]
	s_waitcnt lgkmcnt(3)
	v_mfma_f32_16x16x32_bf16 v[18:21], v[214:217], v[206:209], v[18:21]
	v_mfma_f32_16x16x32_bf16 v[26:29], v[218:221], v[206:209], v[26:29]
	s_waitcnt lgkmcnt(2)
	v_mfma_f32_16x16x32_bf16 v[22:25], v[214:217], v[210:213], v[22:25]
	v_mfma_f32_16x16x32_bf16 v[30:33], v[218:221], v[210:213], v[30:33]
	s_waitcnt lgkmcnt(1)
	v_mfma_f32_16x16x32_bf16 v[34:37], v[222:225], v[198:201], v[34:37]
	v_mfma_f32_16x16x32_bf16 v[38:41], v[222:225], v[202:205], v[38:41]
	v_mfma_f32_16x16x32_bf16 v[2:5], v[222:225], v[206:209], v[2:5]
	v_mfma_f32_16x16x32_bf16 v[6:9], v[222:225], v[210:213], v[6:9]
	s_waitcnt lgkmcnt(0)
	v_mfma_f32_16x16x32_bf16 v[42:45], v[226:229], v[198:201], v[42:45]
	v_mfma_f32_16x16x32_bf16 v[46:49], v[226:229], v[202:205], v[46:49]
	v_mfma_f32_16x16x32_bf16 v[10:13], v[226:229], v[206:209], v[10:13]
	v_mfma_f32_16x16x32_bf16 v[14:17], v[226:229], v[210:213], v[14:17]
	s_nop 7
	s_nop 7
	v_permlane16_swap_b32_e32 v50, v54
	v_permlane16_swap_b32_e32 v51, v55
	v_permlane16_swap_b32_e32 v52, v56
	v_permlane16_swap_b32_e32 v53, v57
	v_permlane16_swap_b32_e32 v58, v62
	v_permlane16_swap_b32_e32 v59, v63
	v_permlane16_swap_b32_e32 v60, v64
	v_permlane16_swap_b32_e32 v61, v65
	v_permlane16_swap_b32_e32 v34, v38
	v_permlane16_swap_b32_e32 v35, v39
	v_permlane16_swap_b32_e32 v36, v40
	v_permlane16_swap_b32_e32 v37, v41
	v_permlane16_swap_b32_e32 v42, v46
	v_permlane16_swap_b32_e32 v43, v47
	v_permlane16_swap_b32_e32 v44, v48
	v_permlane16_swap_b32_e32 v45, v49
	v_permlane16_swap_b32_e32 v18, v22
	v_permlane16_swap_b32_e32 v19, v23
	v_permlane16_swap_b32_e32 v20, v24
	v_permlane16_swap_b32_e32 v21, v25
	v_permlane16_swap_b32_e32 v26, v30
	v_permlane16_swap_b32_e32 v27, v31
	v_permlane16_swap_b32_e32 v28, v32
	v_permlane16_swap_b32_e32 v29, v33
	v_permlane16_swap_b32_e32 v2, v6
	v_permlane16_swap_b32_e32 v3, v7
	v_permlane16_swap_b32_e32 v4, v8
	v_permlane16_swap_b32_e32 v5, v9
	v_permlane16_swap_b32_e32 v10, v14
	v_permlane16_swap_b32_e32 v11, v15
	v_permlane16_swap_b32_e32 v12, v16
	v_permlane16_swap_b32_e32 v13, v17
	v_permlane32_swap_b32_e32 v50, v54
	v_permlane32_swap_b32_e32 v51, v55
	v_permlane32_swap_b32_e32 v52, v56
	v_permlane32_swap_b32_e32 v53, v57
	v_permlane32_swap_b32_e32 v58, v62
	v_permlane32_swap_b32_e32 v59, v63
	v_permlane32_swap_b32_e32 v60, v64
	v_permlane32_swap_b32_e32 v61, v65
	v_permlane32_swap_b32_e32 v34, v38
	v_permlane32_swap_b32_e32 v35, v39
	v_permlane32_swap_b32_e32 v36, v40
	v_permlane32_swap_b32_e32 v37, v41
	v_permlane32_swap_b32_e32 v42, v46
	v_permlane32_swap_b32_e32 v43, v47
	v_permlane32_swap_b32_e32 v44, v48
	v_permlane32_swap_b32_e32 v45, v49
	v_permlane32_swap_b32_e32 v18, v22
	v_permlane32_swap_b32_e32 v19, v23
	v_permlane32_swap_b32_e32 v20, v24
	v_permlane32_swap_b32_e32 v21, v25
	v_permlane32_swap_b32_e32 v26, v30
	v_permlane32_swap_b32_e32 v27, v31
	v_permlane32_swap_b32_e32 v28, v32
	v_permlane32_swap_b32_e32 v29, v33
	v_permlane32_swap_b32_e32 v2, v6
	v_permlane32_swap_b32_e32 v3, v7
	v_permlane32_swap_b32_e32 v4, v8
	v_permlane32_swap_b32_e32 v5, v9
	v_permlane32_swap_b32_e32 v10, v14
	v_permlane32_swap_b32_e32 v11, v15
	v_permlane32_swap_b32_e32 v12, v16
	v_permlane32_swap_b32_e32 v13, v17
	s_waitcnt lgkmcnt(0)
	s_barrier
	s_branch .LBB0_745

; #define MFMA(a, b, c) __builtin_amdgcn_mfma_f32_32x32x16_bf16((a), (b), (c), 0, 0, 0)
; template <bool SWAP, class Epi>
; DI void gemm_tile(const u16* __restrict__ A, int lda, const u16* __restrict__ Bt, int ldb, int K, int m0, int n0, char* smem, Epi&& epi) {
;     ...
;   auto compute = [&](int buf) __attribute__((always_inline)) {
;     bf16x8 af[2][2], bfr[2][2];
;     af[0][0] = *(const bf16x8*)(Asb + buf * 128 * 72);
;     af[0][1] = *(const bf16x8*)(Asb + buf * 128 * 72 + 32 * 72);
;     bfr[0][0] = *(const bf16x8*)(Bsb + buf * 128 * 72);
;     bfr[0][1] = *(const bf16x8*)(Bsb + buf * 128 * 72 + 32 * 72);
; #pragma unroll
;     for (int ks = 0; ks < 4; ++ks) {
;       const int c = ks & 1, n = c ^ 1;
;       if (ks < 3) {
;         af[n][0] = *(const bf16x8*)(Asb + buf * 128 * 72 + (ks + 1) * 16);
;         af[n][1] = *(const bf16x8*)(Asb + buf * 128 * 72 + 32 * 72 + (ks + 1) * 16);
;         bfr[n][0] = *(const bf16x8*)(Bsb + buf * 128 * 72 + (ks + 1) * 16);
;         bfr[n][1] = *(const bf16x8*)(Bsb + buf * 128 * 72 + 32 * 72 + (ks + 1) * 16);
;       }
;       __builtin_amdgcn_sched_barrier(0);
; #pragma unroll
;       for (int mi = 0; mi < 2; ++mi)
; #pragma unroll
;         for (int ni = 0; ni < 2; ++ni) {
;           if (SWAP) acc[mi][ni] = MFMA(bfr[c][ni], af[c][mi], acc[mi][ni]);
;           else acc[mi][ni] = MFMA(af[c][mi], bfr[c][ni], acc[mi][ni]);
;         }
;       __builtin_amdgcn_sched_barrier(0);
;     }
;   };
;   for (int kt = 0; kt < KT; kt += 2) {
;     if (kt + 2 < KT) {
;       const int k0 = (kt + 2) << 6;
; #pragma unroll
;       for (int i = 0; i < 4; ++i) { ra0[i] = *(const u32x4*)(ag + (size_t)i * 32 * lda + k0); rb0[i] = *(const u32x4*)(bg + (size_t)i * 32 * ldb + k0); }
;     }
;     compute(0);
; #pragma unroll
;     for (int i = 0; i < 4; ++i) { *(u32x4*)(asw + 128 * 72 + 32 * i * 72) = ra1[i]; *(u32x4*)(bsw + 128 * 72 + 32 * i * 72) = rb1[i]; }
;     __syncthreads();
;     if (kt + 3 < KT) {
;       const int k0 = (kt + 3) << 6;
; #pragma unroll
;       for (int i = 0; i < 4; ++i) { ra1[i] = *(const u32x4*)(ag + (size_t)i * 32 * lda + k0); rb1[i] = *(const u32x4*)(bg + (size_t)i * 32 * ldb + k0); }
;     }
;     compute(1);
.LBB0_955:
	global_load_dwordx4 v[66:69], v194, s[100:101] offset:256
	global_load_dwordx4 v[70:73], v190, s[98:99] offset:256
	global_load_dwordx4 v[74:77], v195, s[100:101] offset:256
	global_load_dwordx4 v[78:81], v191, s[98:99] offset:256
	global_load_dwordx4 v[82:85], v196, s[100:101] offset:256
	global_load_dwordx4 v[86:89], v192, s[98:99] offset:256
	global_load_dwordx4 v[90:93], v197, s[100:101] offset:256
	global_load_dwordx4 v[94:97], v193, s[98:99] offset:256
	ds_read_b128 v[166:169], v148 offset:36880
	ds_read_b128 v[150:153], v147 offset:16
	ds_read_b128 v[154:157], v147 offset:2320
	ds_read_b128 v[170:173], v148 offset:39184
	ds_read_b128 v[158:161], v147 offset:4624
	ds_read_b128 v[162:165], v147 offset:6928
	ds_read_b128 v[174:177], v148 offset:41488
	ds_read_b128 v[178:181], v148 offset:43792
	s_waitcnt lgkmcnt(6)
	v_mfma_f32_16x16x32_bf16 v[50:53], v[166:169], v[150:153], v[50:53]
	s_waitcnt lgkmcnt(5)
	v_mfma_f32_16x16x32_bf16 v[54:57], v[166:169], v[154:157], v[54:57]
	s_waitcnt lgkmcnt(4)
	v_mfma_f32_16x16x32_bf16 v[58:61], v[170:173], v[150:153], v[58:61]
	v_mfma_f32_16x16x32_bf16 v[62:65], v[170:173], v[154:157], v[62:65]
	ds_read_b128 v[214:217], v148 offset:36944
	ds_read_b128 v[198:201], v147 offset:80
	ds_read_b128 v[202:205], v147 offset:2384
	ds_read_b128 v[218:221], v148 offset:39248
	s_waitcnt lgkmcnt(7)
	v_mfma_f32_16x16x32_bf16 v[18:21], v[166:169], v[158:161], v[18:21]
	v_mfma_f32_16x16x32_bf16 v[26:29], v[170:173], v[158:161], v[26:29]
	s_waitcnt lgkmcnt(6)
	v_mfma_f32_16x16x32_bf16 v[22:25], v[166:169], v[162:165], v[22:25]
	v_mfma_f32_16x16x32_bf16 v[30:33], v[170:173], v[162:165], v[30:33]
	ds_read_b128 v[206:209], v147 offset:4688
	ds_read_b128 v[210:213], v147 offset:6992
	ds_read_b128 v[222:225], v148 offset:41552
	ds_read_b128 v[226:229], v148 offset:43856
	s_waitcnt lgkmcnt(9)
	v_mfma_f32_16x16x32_bf16 v[34:37], v[174:177], v[150:153], v[34:37]
	v_mfma_f32_16x16x32_bf16 v[38:41], v[174:177], v[154:157], v[38:41]
	v_mfma_f32_16x16x32_bf16 v[2:5], v[174:177], v[158:161], v[2:5]
	v_mfma_f32_16x16x32_bf16 v[6:9], v[174:177], v[162:165], v[6:9]
	s_waitcnt lgkmcnt(8)
	v_mfma_f32_16x16x32_bf16 v[42:45], v[178:181], v[150:153], v[42:45]
	v_mfma_f32_16x16x32_bf16 v[46:49], v[178:181], v[154:157], v[46:49]
	s_waitcnt vmcnt(14)
	ds_write_b128 v144, v[98:101] offset:18448
	ds_write_b128 v144, v[102:105] offset:55312
	v_mfma_f32_16x16x32_bf16 v[10:13], v[178:181], v[158:161], v[10:13]
	v_mfma_f32_16x16x32_bf16 v[14:17], v[178:181], v[162:165], v[14:17]
	s_waitcnt lgkmcnt(8)
	v_mfma_f32_16x16x32_bf16 v[50:53], v[214:217], v[198:201], v[50:53]
	s_waitcnt lgkmcnt(7)
	v_mfma_f32_16x16x32_bf16 v[54:57], v[214:217], v[202:205], v[54:57]
	s_waitcnt vmcnt(12)
	ds_write_b128 v144, v[106:109] offset:23056
	ds_write_b128 v144, v[110:113] offset:59920
	s_waitcnt lgkmcnt(8)
	v_mfma_f32_16x16x32_bf16 v[58:61], v[218:221], v[198:201], v[58:61]
	v_mfma_f32_16x16x32_bf16 v[62:65], v[218:221], v[202:205], v[62:65]
	s_waitcnt lgkmcnt(7)
	v_mfma_f32_16x16x32_bf16 v[18:21], v[214:217], v[206:209], v[18:21]
	v_mfma_f32_16x16x32_bf16 v[26:29], v[218:221], v[206:209], v[26:29]
	s_waitcnt vmcnt(10)
	ds_write_b128 v144, v[114:117] offset:27664
	ds_write_b128 v144, v[118:121] offset:64528
	s_waitcnt lgkmcnt(8)
	v_mfma_f32_16x16x32_bf16 v[22:25], v[214:217], v[210:213], v[22:25]
	v_mfma_f32_16x16x32_bf16 v[30:33], v[218:221], v[210:213], v[30:33]
	s_waitcnt lgkmcnt(7)
	v_mfma_f32_16x16x32_bf16 v[34:37], v[222:225], v[198:201], v[34:37]
	v_mfma_f32_16x16x32_bf16 v[38:41], v[222:225], v[202:205], v[38:41]
	s_waitcnt vmcnt(8)
	ds_write_b128 v144, v[122:125] offset:32272
	ds_write_b128 v145, v[126:129] offset:32256
	v_mfma_f32_16x16x32_bf16 v[2:5], v[222:225], v[206:209], v[2:5]
	v_mfma_f32_16x16x32_bf16 v[6:9], v[222:225], v[210:213], v[6:9]
	s_waitcnt lgkmcnt(8)
	v_mfma_f32_16x16x32_bf16 v[42:45], v[226:229], v[198:201], v[42:45]
	v_mfma_f32_16x16x32_bf16 v[46:49], v[226:229], v[202:205], v[46:49]
	v_mfma_f32_16x16x32_bf16 v[10:13], v[226:229], v[206:209], v[10:13]
	v_mfma_f32_16x16x32_bf16 v[14:17], v[226:229], v[210:213], v[14:17]
	s_waitcnt lgkmcnt(0)
	s_barrier
	global_load_dwordx4 v[98:101], v194, s[100:101] offset:384
	global_load_dwordx4 v[102:105], v190, s[98:99] offset:384
	global_load_dwordx4 v[106:109], v195, s[100:101] offset:384
	global_load_dwordx4 v[110:113], v191, s[98:99] offset:384
	global_load_dwordx4 v[114:117], v196, s[100:101] offset:384
	global_load_dwordx4 v[118:121], v192, s[98:99] offset:384
	global_load_dwordx4 v[122:125], v197, s[100:101] offset:384
	global_load_dwordx4 v[126:129], v193, s[98:99] offset:384
	ds_read_b128 v[166:169], v148 offset:55312
	ds_read_b128 v[150:153], v147 offset:18448
	ds_read_b128 v[154:157], v147 offset:20752
	ds_read_b128 v[170:173], v148 offset:57616
	ds_read_b128 v[158:161], v147 offset:23056
	ds_read_b128 v[162:165], v147 offset:25360
	ds_read_b128 v[174:177], v148 offset:59920
	ds_read_b128 v[178:181], v148 offset:62224
	s_waitcnt lgkmcnt(6)
	v_mfma_f32_16x16x32_bf16 v[50:53], v[166:169], v[150:153], v[50:53]
	s_waitcnt lgkmcnt(5)
	v_mfma_f32_16x16x32_bf16 v[54:57], v[166:169], v[154:157], v[54:57]
	s_waitcnt lgkmcnt(4)
	v_mfma_f32_16x16x32_bf16 v[58:61], v[170:173], v[150:153], v[58:61]
	v_mfma_f32_16x16x32_bf16 v[62:65], v[170:173], v[154:157], v[62:65]
	ds_read_b128 v[214:217], v148 offset:55376
	ds_read_b128 v[198:201], v147 offset:18512
	ds_read_b128 v[202:205], v147 offset:20816
	ds_read_b128 v[218:221], v148 offset:57680
	s_waitcnt lgkmcnt(7)
	v_mfma_f32_16x16x32_bf16 v[18:21], v[166:169], v[158:161], v[18:21]
	v_mfma_f32_16x16x32_bf16 v[26:29], v[170:173], v[158:161], v[26:29]
	s_waitcnt lgkmcnt(6)
; #define MFMA(a, b, c) __builtin_amdgcn_mfma_f32_32x32x16_bf16((a), (b), (c), 0, 0, 0)
; template <bool SWAP, class Epi>
; DI void gemm_tile(const u16* __restrict__ A, int lda, const u16* __restrict__ Bt, int ldb, int K, int m0, int n0, char* smem, Epi&& epi) {
;     ...
;   auto compute = [&](int buf) __attribute__((always_inline)) {
;     bf16x8 af[2][2], bfr[2][2];
;     af[0][0] = *(const bf16x8*)(Asb + buf * 128 * 72);
;     af[0][1] = *(const bf16x8*)(Asb + buf * 128 * 72 + 32 * 72);
;     bfr[0][0] = *(const bf16x8*)(Bsb + buf * 128 * 72);
;     bfr[0][1] = *(const bf16x8*)(Bsb + buf * 128 * 72 + 32 * 72);
; #pragma unroll
;     for (int ks = 0; ks < 4; ++ks) {
;       const int c = ks & 1, n = c ^ 1;
;       if (ks < 3) {
;         af[n][0] = *(const bf16x8*)(Asb + buf * 128 * 72 + (ks + 1) * 16);
;         af[n][1] = *(const bf16x8*)(Asb + buf * 128 * 72 + 32 * 72 + (ks + 1) * 16);
;         bfr[n][0] = *(const bf16x8*)(Bsb + buf * 128 * 72 + (ks + 1) * 16);
;         bfr[n][1] = *(const bf16x8*)(Bsb + buf * 128 * 72 + 32 * 72 + (ks + 1) * 16);
;       }
;       __builtin_amdgcn_sched_barrier(0);
; #pragma unroll
;       for (int mi = 0; mi < 2; ++mi)
; #pragma unroll
;         for (int ni = 0; ni < 2; ++ni) {
;           if (SWAP) acc[mi][ni] = MFMA(bfr[c][ni], af[c][mi], acc[mi][ni]);
;           else acc[mi][ni] = MFMA(af[c][mi], bfr[c][ni], acc[mi][ni]);
;         }
;       __builtin_amdgcn_sched_barrier(0);
;     }
;   };
;   for (int kt = 0; kt < KT; kt += 2) {
;     if (kt + 2 < KT) {
;       const int k0 = (kt + 2) << 6;
; #pragma unroll
;       for (int i = 0; i < 4; ++i) { ra0[i] = *(const u32x4*)(ag + (size_t)i * 32 * lda + k0); rb0[i] = *(const u32x4*)(bg + (size_t)i * 32 * ldb + k0); }
;     }
;     compute(0);
; #pragma unroll
;     for (int i = 0; i < 4; ++i) { *(u32x4*)(asw + 128 * 72 + 32 * i * 72) = ra1[i]; *(u32x4*)(bsw + 128 * 72 + 32 * i * 72) = rb1[i]; }
;     __syncthreads();
;     if (kt + 3 < KT) {
;       const int k0 = (kt + 3) << 6;
; #pragma unroll
;       for (int i = 0; i < 4; ++i) { ra1[i] = *(const u32x4*)(ag + (size_t)i * 32 * lda + k0); rb1[i] = *(const u32x4*)(bg + (size_t)i * 32 * ldb + k0); }
;     }
;     compute(1);
;     if (kt + 2 < KT) {
; #pragma unroll
;       for (int i = 0; i < 4; ++i) { *(u32x4*)(asw + 32 * i * 72) = ra0[i]; *(u32x4*)(bsw + 32 * i * 72) = rb0[i]; }
;     }
;     __syncthreads();
;   }
	v_mfma_f32_16x16x32_bf16 v[22:25], v[166:169], v[162:165], v[22:25]
	v_mfma_f32_16x16x32_bf16 v[30:33], v[170:173], v[162:165], v[30:33]
	ds_read_b128 v[206:209], v147 offset:23120
	ds_read_b128 v[210:213], v147 offset:25424
	ds_read_b128 v[222:225], v148 offset:59984
	ds_read_b128 v[226:229], v148 offset:62288
	s_waitcnt lgkmcnt(9)
	v_mfma_f32_16x16x32_bf16 v[34:37], v[174:177], v[150:153], v[34:37]
	v_mfma_f32_16x16x32_bf16 v[38:41], v[174:177], v[154:157], v[38:41]
	v_mfma_f32_16x16x32_bf16 v[2:5], v[174:177], v[158:161], v[2:5]
	v_mfma_f32_16x16x32_bf16 v[6:9], v[174:177], v[162:165], v[6:9]
	s_waitcnt lgkmcnt(8)
	v_mfma_f32_16x16x32_bf16 v[42:45], v[178:181], v[150:153], v[42:45]
	v_mfma_f32_16x16x32_bf16 v[46:49], v[178:181], v[154:157], v[46:49]
	s_waitcnt vmcnt(14)
	ds_write_b128 v144, v[66:69] offset:16
	ds_write_b128 v144, v[70:73] offset:36880
	v_mfma_f32_16x16x32_bf16 v[10:13], v[178:181], v[158:161], v[10:13]
	v_mfma_f32_16x16x32_bf16 v[14:17], v[178:181], v[162:165], v[14:17]
	s_waitcnt lgkmcnt(8)
	v_mfma_f32_16x16x32_bf16 v[50:53], v[214:217], v[198:201], v[50:53]
	s_waitcnt lgkmcnt(7)
	v_mfma_f32_16x16x32_bf16 v[54:57], v[214:217], v[202:205], v[54:57]
	s_waitcnt vmcnt(12)
	ds_write_b128 v144, v[74:77] offset:4624
	ds_write_b128 v144, v[78:81] offset:41488
	s_waitcnt lgkmcnt(8)
	v_mfma_f32_16x16x32_bf16 v[58:61], v[218:221], v[198:201], v[58:61]
	v_mfma_f32_16x16x32_bf16 v[62:65], v[218:221], v[202:205], v[62:65]
	s_waitcnt lgkmcnt(7)
	v_mfma_f32_16x16x32_bf16 v[18:21], v[214:217], v[206:209], v[18:21]
	v_mfma_f32_16x16x32_bf16 v[26:29], v[218:221], v[206:209], v[26:29]
	s_waitcnt vmcnt(10)
	ds_write_b128 v144, v[82:85] offset:9232
	ds_write_b128 v144, v[86:89] offset:46096
	s_waitcnt lgkmcnt(8)
	v_mfma_f32_16x16x32_bf16 v[22:25], v[214:217], v[210:213], v[22:25]
	v_mfma_f32_16x16x32_bf16 v[30:33], v[218:221], v[210:213], v[30:33]
	s_waitcnt lgkmcnt(7)
	v_mfma_f32_16x16x32_bf16 v[34:37], v[222:225], v[198:201], v[34:37]
	v_mfma_f32_16x16x32_bf16 v[38:41], v[222:225], v[202:205], v[38:41]
	s_waitcnt vmcnt(8)
	ds_write_b128 v144, v[90:93] offset:13840
	ds_write_b128 v144, v[94:97] offset:50704
	v_mfma_f32_16x16x32_bf16 v[2:5], v[222:225], v[206:209], v[2:5]
	v_mfma_f32_16x16x32_bf16 v[6:9], v[222:225], v[210:213], v[6:9]
	s_waitcnt lgkmcnt(8)
	v_mfma_f32_16x16x32_bf16 v[42:45], v[226:229], v[198:201], v[42:45]
	v_mfma_f32_16x16x32_bf16 v[46:49], v[226:229], v[202:205], v[46:49]
	v_mfma_f32_16x16x32_bf16 v[10:13], v[226:229], v[206:209], v[10:13]
	v_mfma_f32_16x16x32_bf16 v[14:17], v[226:229], v[210:213], v[14:17]
	s_add_i32 s18, s18, 2
	s_add_u32 s98, s98, 256
	s_addc_u32 s99, s99, 0
	s_add_u32 s100, s100, 256
	s_addc_u32 s101, s101, 0
	s_waitcnt lgkmcnt(0)
	s_barrier
	s_cmp_lt_u32 s18, 30
	s_cbranch_scc1 .LBB0_955
	ds_read_b128 v[166:169], v148 offset:36880
	ds_read_b128 v[150:153], v147 offset:16
	ds_read_b128 v[154:157], v147 offset:2320
	ds_read_b128 v[170:173], v148 offset:39184
	ds_read_b128 v[158:161], v147 offset:4624
	ds_read_b128 v[162:165], v147 offset:6928
	ds_read_b128 v[174:177], v148 offset:41488
	ds_read_b128 v[178:181], v148 offset:43792
	s_waitcnt lgkmcnt(6)
	v_mfma_f32_16x16x32_bf16 v[50:53], v[166:169], v[150:153], v[50:53]
	s_waitcnt lgkmcnt(5)
	v_mfma_f32_16x16x32_bf16 v[54:57], v[166:169], v[154:157], v[54:57]
	s_waitcnt lgkmcnt(4)
	v_mfma_f32_16x16x32_bf16 v[58:61], v[170:173], v[150:153], v[58:61]
	v_mfma_f32_16x16x32_bf16 v[62:65], v[170:173], v[154:157], v[62:65]
	ds_read_b128 v[214:217], v148 offset:36944
	ds_read_b128 v[198:201], v147 offset:80
	ds_read_b128 v[202:205], v147 offset:2384
	ds_read_b128 v[218:221], v148 offset:39248
	s_waitcnt lgkmcnt(7)
	v_mfma_f32_16x16x32_bf16 v[18:21], v[166:169], v[158:161], v[18:21]
	v_mfma_f32_16x16x32_bf16 v[26:29], v[170:173], v[158:161], v[26:29]
	s_waitcnt lgkmcnt(6)
	v_mfma_f32_16x16x32_bf16 v[22:25], v[166:169], v[162:165], v[22:25]
	v_mfma_f32_16x16x32_bf16 v[30:33], v[170:173], v[162:165], v[30:33]
	ds_read_b128 v[206:209], v147 offset:4688
	ds_read_b128 v[210:213], v147 offset:6992
	ds_read_b128 v[222:225], v148 offset:41552
	ds_read_b128 v[226:229], v148 offset:43856
	s_waitcnt lgkmcnt(9)
	v_mfma_f32_16x16x32_bf16 v[34:37], v[174:177], v[150:153], v[34:37]
	v_mfma_f32_16x16x32_bf16 v[38:41], v[174:177], v[154:157], v[38:41]
	v_mfma_f32_16x16x32_bf16 v[2:5], v[174:177], v[158:161], v[2:5]
	v_mfma_f32_16x16x32_bf16 v[6:9], v[174:177], v[162:165], v[6:9]
	s_waitcnt lgkmcnt(8)
	v_mfma_f32_16x16x32_bf16 v[42:45], v[178:181], v[150:153], v[42:45]
	v_mfma_f32_16x16x32_bf16 v[46:49], v[178:181], v[154:157], v[46:49]
	s_waitcnt vmcnt(6)
	ds_write_b128 v144, v[98:101] offset:18448
	ds_write_b128 v144, v[102:105] offset:55312
	v_mfma_f32_16x16x32_bf16 v[10:13], v[178:181], v[158:161], v[10:13]
	v_mfma_f32_16x16x32_bf16 v[14:17], v[178:181], v[162:165], v[14:17]
	s_waitcnt lgkmcnt(8)
	v_mfma_f32_16x16x32_bf16 v[50:53], v[214:217], v[198:201], v[50:53]
	s_waitcnt lgkmcnt(7)
	v_mfma_f32_16x16x32_bf16 v[54:57], v[214:217], v[202:205], v[54:57]
	s_waitcnt vmcnt(4)
	ds_write_b128 v144, v[106:109] offset:23056
	ds_write_b128 v144, v[110:113] offset:59920
	s_waitcnt lgkmcnt(8)
	v_mfma_f32_16x16x32_bf16 v[58:61], v[218:221], v[198:201], v[58:61]
	v_mfma_f32_16x16x32_bf16 v[62:65], v[218:221], v[202:205], v[62:65]
	s_waitcnt lgkmcnt(7)
	v_mfma_f32_16x16x32_bf16 v[18:21], v[214:217], v[206:209], v[18:21]
	v_mfma_f32_16x16x32_bf16 v[26:29], v[218:221], v[206:209], v[26:29]
	s_waitcnt vmcnt(2)
	ds_write_b128 v144, v[114:117] offset:27664
	ds_write_b128 v144, v[118:121] offset:64528
	s_waitcnt lgkmcnt(8)
	v_mfma_f32_16x16x32_bf16 v[22:25], v[214:217], v[210:213], v[22:25]
	v_mfma_f32_16x16x32_bf16 v[30:33], v[218:221], v[210:213], v[30:33]
	s_waitcnt lgkmcnt(7)
	v_mfma_f32_16x16x32_bf16 v[34:37], v[222:225], v[198:201], v[34:37]
	v_mfma_f32_16x16x32_bf16 v[38:41], v[222:225], v[202:205], v[38:41]
	s_waitcnt vmcnt(0)
	ds_write_b128 v144, v[122:125] offset:32272
	ds_write_b128 v145, v[126:129] offset:32256
	v_mfma_f32_16x16x32_bf16 v[2:5], v[222:225], v[206:209], v[2:5]
	v_mfma_f32_16x16x32_bf16 v[6:9], v[222:225], v[210:213], v[6:9]
	s_waitcnt lgkmcnt(8)
	v_mfma_f32_16x16x32_bf16 v[42:45], v[226:229], v[198:201], v[42:45]
	v_mfma_f32_16x16x32_bf16 v[46:49], v[226:229], v[202:205], v[46:49]
	v_mfma_f32_16x16x32_bf16 v[10:13], v[226:229], v[206:209], v[10:13]
	v_mfma_f32_16x16x32_bf16 v[14:17], v[226:229], v[210:213], v[14:17]
	s_waitcnt lgkmcnt(0)
	s_barrier
; #define MFMA(a, b, c) __builtin_amdgcn_mfma_f32_32x32x16_bf16((a), (b), (c), 0, 0, 0)
; template <bool SWAP, class Epi>
; DI void gemm_tile(const u16* __restrict__ A, int lda, const u16* __restrict__ Bt, int ldb, int K, int m0, int n0, char* smem, Epi&& epi) {
;     ...
;   auto compute = [&](int buf) __attribute__((always_inline)) {
;     bf16x8 af[2][2], bfr[2][2];
;     af[0][0] = *(const bf16x8*)(Asb + buf * 128 * 72);
;     af[0][1] = *(const bf16x8*)(Asb + buf * 128 * 72 + 32 * 72);
;     bfr[0][0] = *(const bf16x8*)(Bsb + buf * 128 * 72);
;     bfr[0][1] = *(const bf16x8*)(Bsb + buf * 128 * 72 + 32 * 72);
; #pragma unroll
;     for (int ks = 0; ks < 4; ++ks) {
;       const int c = ks & 1, n = c ^ 1;
;       if (ks < 3) {
;         af[n][0] = *(const bf16x8*)(Asb + buf * 128 * 72 + (ks + 1) * 16);
;         af[n][1] = *(const bf16x8*)(Asb + buf * 128 * 72 + 32 * 72 + (ks + 1) * 16);
;         bfr[n][0] = *(const bf16x8*)(Bsb + buf * 128 * 72 + (ks + 1) * 16);
;         bfr[n][1] = *(const bf16x8*)(Bsb + buf * 128 * 72 + 32 * 72 + (ks + 1) * 16);
;       }
;       __builtin_amdgcn_sched_barrier(0);
; #pragma unroll
;       for (int mi = 0; mi < 2; ++mi)
; #pragma unroll
;         for (int ni = 0; ni < 2; ++ni) {
;           if (SWAP) acc[mi][ni] = MFMA(bfr[c][ni], af[c][mi], acc[mi][ni]);
;           else acc[mi][ni] = MFMA(af[c][mi], bfr[c][ni], acc[mi][ni]);
;         }
;       __builtin_amdgcn_sched_barrier(0);
;     }
;   };
;     ...
;     compute(1);
;     if (kt + 2 < KT) {
; #pragma unroll
;       for (int i = 0; i < 4; ++i) { *(u32x4*)(asw + 32 * i * 72) = ra0[i]; *(u32x4*)(bsw + 32 * i * 72) = rb0[i]; }
;     }
;     __syncthreads();
	ds_read_b128 v[166:169], v148 offset:55312
	ds_read_b128 v[150:153], v147 offset:18448
	ds_read_b128 v[154:157], v147 offset:20752
	ds_read_b128 v[170:173], v148 offset:57616
	ds_read_b128 v[158:161], v147 offset:23056
	ds_read_b128 v[162:165], v147 offset:25360
	ds_read_b128 v[174:177], v148 offset:59920
	ds_read_b128 v[178:181], v148 offset:62224
	s_waitcnt lgkmcnt(6)
	v_mfma_f32_16x16x32_bf16 v[50:53], v[166:169], v[150:153], v[50:53]
	s_waitcnt lgkmcnt(5)
	v_mfma_f32_16x16x32_bf16 v[54:57], v[166:169], v[154:157], v[54:57]
	s_waitcnt lgkmcnt(4)
	v_mfma_f32_16x16x32_bf16 v[58:61], v[170:173], v[150:153], v[58:61]
	v_mfma_f32_16x16x32_bf16 v[62:65], v[170:173], v[154:157], v[62:65]
	ds_read_b128 v[214:217], v148 offset:55376
	ds_read_b128 v[198:201], v147 offset:18512
	ds_read_b128 v[202:205], v147 offset:20816
	ds_read_b128 v[218:221], v148 offset:57680
	s_waitcnt lgkmcnt(7)
	v_mfma_f32_16x16x32_bf16 v[18:21], v[166:169], v[158:161], v[18:21]
	v_mfma_f32_16x16x32_bf16 v[26:29], v[170:173], v[158:161], v[26:29]
	s_waitcnt lgkmcnt(6)
	v_mfma_f32_16x16x32_bf16 v[22:25], v[166:169], v[162:165], v[22:25]
	v_mfma_f32_16x16x32_bf16 v[30:33], v[170:173], v[162:165], v[30:33]
	ds_read_b128 v[206:209], v147 offset:23120
	ds_read_b128 v[210:213], v147 offset:25424
	ds_read_b128 v[222:225], v148 offset:59984
	ds_read_b128 v[226:229], v148 offset:62288
	s_waitcnt lgkmcnt(9)
	v_mfma_f32_16x16x32_bf16 v[34:37], v[174:177], v[150:153], v[34:37]
	v_mfma_f32_16x16x32_bf16 v[38:41], v[174:177], v[154:157], v[38:41]
	v_mfma_f32_16x16x32_bf16 v[2:5], v[174:177], v[158:161], v[2:5]
	v_mfma_f32_16x16x32_bf16 v[6:9], v[174:177], v[162:165], v[6:9]
	s_waitcnt lgkmcnt(8)
	v_mfma_f32_16x16x32_bf16 v[42:45], v[178:181], v[150:153], v[42:45]
	v_mfma_f32_16x16x32_bf16 v[46:49], v[178:181], v[154:157], v[46:49]
	v_mfma_f32_16x16x32_bf16 v[10:13], v[178:181], v[158:161], v[10:13]
	v_mfma_f32_16x16x32_bf16 v[14:17], v[178:181], v[162:165], v[14:17]
	s_waitcnt lgkmcnt(6)
	v_mfma_f32_16x16x32_bf16 v[50:53], v[214:217], v[198:201], v[50:53]
	s_waitcnt lgkmcnt(5)
	v_mfma_f32_16x16x32_bf16 v[54:57], v[214:217], v[202:205], v[54:57]
	s_waitcnt lgkmcnt(4)
	v_mfma_f32_16x16x32_bf16 v[58:61], v[218:221], v[198:201], v[58:61]
	v_mfma_f32_16x16x32_bf16 v[62:65], v[218:221], v[202:205], v[62:65]
	s_waitcnt lgkmcnt(3)
	v_mfma_f32_16x16x32_bf16 v[18:21], v[214:217], v[206:209], v[18:21]
	v_mfma_f32_16x16x32_bf16 v[26:29], v[218:221], v[206:209], v[26:29]
	s_waitcnt lgkmcnt(2)
	v_mfma_f32_16x16x32_bf16 v[22:25], v[214:217], v[210:213], v[22:25]
	v_mfma_f32_16x16x32_bf16 v[30:33], v[218:221], v[210:213], v[30:33]
	s_waitcnt lgkmcnt(1)
	v_mfma_f32_16x16x32_bf16 v[34:37], v[222:225], v[198:201], v[34:37]
	v_mfma_f32_16x16x32_bf16 v[38:41], v[222:225], v[202:205], v[38:41]
	v_mfma_f32_16x16x32_bf16 v[2:5], v[222:225], v[206:209], v[2:5]
	v_mfma_f32_16x16x32_bf16 v[6:9], v[222:225], v[210:213], v[6:9]
	s_waitcnt lgkmcnt(0)
	v_mfma_f32_16x16x32_bf16 v[42:45], v[226:229], v[198:201], v[42:45]
	v_mfma_f32_16x16x32_bf16 v[46:49], v[226:229], v[202:205], v[46:49]
	v_mfma_f32_16x16x32_bf16 v[10:13], v[226:229], v[206:209], v[10:13]
	v_mfma_f32_16x16x32_bf16 v[14:17], v[226:229], v[210:213], v[14:17]
	s_nop 7
	s_nop 7
	v_permlane16_swap_b32_e32 v50, v54
	v_permlane16_swap_b32_e32 v51, v55
	v_permlane16_swap_b32_e32 v52, v56
	v_permlane16_swap_b32_e32 v53, v57
	v_permlane16_swap_b32_e32 v58, v62
	v_permlane16_swap_b32_e32 v59, v63
	v_permlane16_swap_b32_e32 v60, v64
	v_permlane16_swap_b32_e32 v61, v65
	v_permlane16_swap_b32_e32 v34, v38
	v_permlane16_swap_b32_e32 v35, v39
	v_permlane16_swap_b32_e32 v36, v40
	v_permlane16_swap_b32_e32 v37, v41
	v_permlane16_swap_b32_e32 v42, v46
	v_permlane16_swap_b32_e32 v43, v47
	v_permlane16_swap_b32_e32 v44, v48
	v_permlane16_swap_b32_e32 v45, v49
	v_permlane16_swap_b32_e32 v18, v22
	v_permlane16_swap_b32_e32 v19, v23
	v_permlane16_swap_b32_e32 v20, v24
	v_permlane16_swap_b32_e32 v21, v25
	v_permlane16_swap_b32_e32 v26, v30
	v_permlane16_swap_b32_e32 v27, v31
	v_permlane16_swap_b32_e32 v28, v32
	v_permlane16_swap_b32_e32 v29, v33
	v_permlane16_swap_b32_e32 v2, v6
	v_permlane16_swap_b32_e32 v3, v7
	v_permlane16_swap_b32_e32 v4, v8
	v_permlane16_swap_b32_e32 v5, v9
	v_permlane16_swap_b32_e32 v10, v14
	v_permlane16_swap_b32_e32 v11, v15
	v_permlane16_swap_b32_e32 v12, v16
	v_permlane16_swap_b32_e32 v13, v17
	v_permlane32_swap_b32_e32 v50, v54
	v_permlane32_swap_b32_e32 v51, v55
	v_permlane32_swap_b32_e32 v52, v56
	v_permlane32_swap_b32_e32 v53, v57
	v_permlane32_swap_b32_e32 v58, v62
	v_permlane32_swap_b32_e32 v59, v63
	v_permlane32_swap_b32_e32 v60, v64
	v_permlane32_swap_b32_e32 v61, v65
	v_permlane32_swap_b32_e32 v34, v38
	v_permlane32_swap_b32_e32 v35, v39
	v_permlane32_swap_b32_e32 v36, v40
	v_permlane32_swap_b32_e32 v37, v41
	v_permlane32_swap_b32_e32 v42, v46
	v_permlane32_swap_b32_e32 v43, v47
	v_permlane32_swap_b32_e32 v44, v48
	v_permlane32_swap_b32_e32 v45, v49
	v_permlane32_swap_b32_e32 v18, v22
	v_permlane32_swap_b32_e32 v19, v23
	v_permlane32_swap_b32_e32 v20, v24
	v_permlane32_swap_b32_e32 v21, v25
	v_permlane32_swap_b32_e32 v26, v30
	v_permlane32_swap_b32_e32 v27, v31
	v_permlane32_swap_b32_e32 v28, v32
	v_permlane32_swap_b32_e32 v29, v33
	v_permlane32_swap_b32_e32 v2, v6
	v_permlane32_swap_b32_e32 v3, v7
	v_permlane32_swap_b32_e32 v4, v8
	v_permlane32_swap_b32_e32 v5, v9
	v_permlane32_swap_b32_e32 v10, v14
	v_permlane32_swap_b32_e32 v11, v15
	v_permlane32_swap_b32_e32 v12, v16
	v_permlane32_swap_b32_e32 v13, v17
	s_waitcnt lgkmcnt(0)
	s_barrier
	s_branch .LBB0_952
